# gates epilogue: the 63 divergent om = (x > -0.02 ? poly : 1 - exp(x)) blocks made branch-free (both sides + v_cndmask)
# baseline (speedup 1.0000x reference)
.LBB0_1086:
	s_lshl_b32 s0, s29, 14
	s_ashr_i32 s1, s0, 31
	v_lshl_add_u64 v[52:53], s[0:1], 1, v[72:73]
	s_mov_b64 s[0:1], 0x2740000
	s_waitcnt vmcnt(0)
	v_lshl_add_u64 v[4:5], v[52:53], 0, s[0:1]
	v_lshlrev_b64 v[54:55], 1, v[80:81]
	v_lshl_add_u64 v[0:1], v[4:5], 0, v[54:55]
	global_load_dwordx4 v[0:3], v[0:1], off
	v_lshlrev_b64 v[56:57], 1, v[82:83]
	v_lshlrev_b64 v[58:59], 1, v[84:85]
	v_lshlrev_b64 v[60:61], 1, v[86:87]
	v_lshlrev_b64 v[62:63], 1, v[88:89]
	v_lshlrev_b64 v[64:65], 1, v[90:91]
	v_lshlrev_b64 v[66:67], 1, v[92:93]
	v_lshlrev_b64 v[68:69], 1, v[94:95]
	s_ashr_i32 s23, s22, 31
	v_lshl_add_u64 v[70:71], s[22:23], 2, v[78:79]
	s_mov_b64 s[0:1], 0x2790000
	v_lshl_add_u64 v[8:9], v[4:5], 0, v[56:57]
	global_load_dwordx4 v[8:11], v[8:9], off
	v_lshl_add_u64 v[12:13], v[4:5], 0, v[58:59]
	global_load_dwordx4 v[12:15], v[12:13], off
	v_lshl_add_u64 v[16:17], v[4:5], 0, v[60:61]
	global_load_dwordx4 v[16:19], v[16:17], off
	v_lshl_add_u64 v[20:21], v[4:5], 0, v[62:63]
	global_load_dwordx4 v[20:23], v[20:21], off
	v_lshl_add_u64 v[24:25], v[4:5], 0, v[64:65]
	global_load_dwordx4 v[24:27], v[24:25], off
	v_lshl_add_u64 v[28:29], v[4:5], 0, v[66:67]
	global_load_dwordx4 v[28:31], v[28:29], off
	v_lshl_add_u64 v[32:33], v[4:5], 0, v[68:69]
	global_load_dwordx4 v[32:35], v[32:33], off
	s_waitcnt vmcnt(7)
	ds_write_b128 v120, v[0:3] offset:32768
	s_waitcnt vmcnt(6)
	ds_write_b128 v121, v[8:11] offset:32768
	s_waitcnt vmcnt(5)
	ds_write_b128 v122, v[12:15] offset:32768
	s_waitcnt vmcnt(4)
	ds_write_b128 v123, v[16:19] offset:32768
	s_waitcnt vmcnt(3)
	ds_write_b128 v124, v[20:23] offset:32768
	s_waitcnt vmcnt(2)
	ds_write_b128 v125, v[24:27] offset:32768
	s_waitcnt vmcnt(1)
	ds_write_b128 v126, v[28:31] offset:32768
	s_waitcnt vmcnt(0)
	ds_write_b128 v127, v[32:35] offset:32768
	s_waitcnt lgkmcnt(0)
	s_barrier
	ds_read_b128 v[0:3], v116
	ds_read_b128 v[4:7], v116 offset:2048
	ds_read_b128 v[8:11], v116 offset:4096
	ds_read_b128 v[12:15], v116 offset:6144
	ds_read_b128 v[16:19], v117 offset:32768
	ds_read_b128 v[20:23], v117 offset:34816
	ds_read_b128 v[24:27], v117 offset:36864
	ds_read_b128 v[28:31], v117 offset:38912
	s_waitcnt lgkmcnt(3)
	v_mfma_f32_16x16x32_bf16 v[32:35], v[16:19], v[0:3], 0
	s_waitcnt lgkmcnt(2)
	v_mfma_f32_16x16x32_bf16 v[36:39], v[20:23], v[0:3], 0
	s_waitcnt lgkmcnt(1)
	v_mfma_f32_16x16x32_bf16 v[40:43], v[24:27], v[0:3], 0
	s_waitcnt lgkmcnt(0)
	v_mfma_f32_16x16x32_bf16 v[0:3], v[28:31], v[0:3], 0
	v_mfma_f32_16x16x32_bf16 v[44:47], v[16:19], v[4:7], 0
	v_mfma_f32_16x16x32_bf16 v[48:51], v[20:23], v[4:7], 0
	v_mfma_f32_16x16x32_bf16 v[96:99], v[24:27], v[4:7], 0
	v_mfma_f32_16x16x32_bf16 v[4:7], v[28:31], v[4:7], 0
	v_mfma_f32_16x16x32_bf16 v[100:103], v[16:19], v[8:11], 0
	v_mfma_f32_16x16x32_bf16 v[128:131], v[20:23], v[8:11], 0
	v_mfma_f32_16x16x32_bf16 v[132:135], v[24:27], v[8:11], 0
	v_mfma_f32_16x16x32_bf16 v[8:11], v[28:31], v[8:11], 0
	v_mfma_f32_16x16x32_bf16 v[16:19], v[16:19], v[12:15], 0
	v_mfma_f32_16x16x32_bf16 v[20:23], v[20:23], v[12:15], 0
	v_mfma_f32_16x16x32_bf16 v[24:27], v[24:27], v[12:15], 0
	v_mfma_f32_16x16x32_bf16 v[12:15], v[28:31], v[12:15], 0
	ds_read_b128 v[28:31], v118
	ds_read_b128 v[136:139], v118 offset:2048
	ds_read_b128 v[140:143], v118 offset:4096
	ds_read_b128 v[144:147], v118 offset:6144
	ds_read_b128 v[148:151], v119 offset:32768
	ds_read_b128 v[152:155], v119 offset:34816
	ds_read_b128 v[156:159], v119 offset:36864
	ds_read_b128 v[160:163], v119 offset:38912
	s_waitcnt lgkmcnt(3)
	v_mfma_f32_16x16x32_bf16 v[32:35], v[148:151], v[28:31], v[32:35]
	s_waitcnt lgkmcnt(2)
	v_mfma_f32_16x16x32_bf16 v[36:39], v[152:155], v[28:31], v[36:39]
	s_waitcnt lgkmcnt(1)
	v_mfma_f32_16x16x32_bf16 v[40:43], v[156:159], v[28:31], v[40:43]
	s_waitcnt lgkmcnt(0)
	v_mfma_f32_16x16x32_bf16 v[0:3], v[160:163], v[28:31], v[0:3]
	v_mfma_f32_16x16x32_bf16 v[28:31], v[148:151], v[136:139], v[44:47]
	v_mfma_f32_16x16x32_bf16 v[44:47], v[152:155], v[136:139], v[48:51]
	v_mfma_f32_16x16x32_bf16 v[48:51], v[156:159], v[136:139], v[96:99]
	v_mfma_f32_16x16x32_bf16 v[4:7], v[160:163], v[136:139], v[4:7]
	v_mfma_f32_16x16x32_bf16 v[96:99], v[148:151], v[140:143], v[100:103]
	v_mfma_f32_16x16x32_bf16 v[100:103], v[152:155], v[140:143], v[128:131]
	v_mfma_f32_16x16x32_bf16 v[128:131], v[156:159], v[140:143], v[132:135]
	v_mfma_f32_16x16x32_bf16 v[8:11], v[160:163], v[140:143], v[8:11]
	v_mfma_f32_16x16x32_bf16 v[16:19], v[148:151], v[144:147], v[16:19]
	v_mfma_f32_16x16x32_bf16 v[20:23], v[152:155], v[144:147], v[20:23]
	v_mfma_f32_16x16x32_bf16 v[24:27], v[156:159], v[144:147], v[24:27]
	v_mfma_f32_16x16x32_bf16 v[12:15], v[160:163], v[144:147], v[12:15]
	ds_read_b128 v[132:135], v116 offset:16384
	ds_read_b128 v[136:139], v116 offset:18432
	ds_read_b128 v[140:143], v116 offset:20480
	ds_read_b128 v[144:147], v116 offset:22528
	ds_read_b128 v[148:151], v117 offset:49152
	ds_read_b128 v[152:155], v117 offset:51200
	ds_read_b128 v[156:159], v117 offset:53248
	ds_read_b128 v[160:163], v117 offset:55296
	s_waitcnt lgkmcnt(3)
	v_mfma_f32_16x16x32_bf16 v[32:35], v[148:151], v[132:135], v[32:35]
	s_waitcnt lgkmcnt(2)
	v_mfma_f32_16x16x32_bf16 v[36:39], v[152:155], v[132:135], v[36:39]
	s_waitcnt lgkmcnt(1)
	v_mfma_f32_16x16x32_bf16 v[40:43], v[156:159], v[132:135], v[40:43]
	s_waitcnt lgkmcnt(0)
	v_mfma_f32_16x16x32_bf16 v[0:3], v[160:163], v[132:135], v[0:3]
	v_mfma_f32_16x16x32_bf16 v[132:135], v[148:151], v[136:139], v[28:31]
	v_mfma_f32_16x16x32_bf16 v[164:167], v[152:155], v[136:139], v[44:47]
	v_mfma_f32_16x16x32_bf16 v[48:51], v[156:159], v[136:139], v[48:51]
	v_mfma_f32_16x16x32_bf16 v[4:7], v[160:163], v[136:139], v[4:7]
	v_mfma_f32_16x16x32_bf16 v[96:99], v[148:151], v[140:143], v[96:99]
	v_mfma_f32_16x16x32_bf16 v[100:103], v[152:155], v[140:143], v[100:103]
	v_mfma_f32_16x16x32_bf16 v[128:131], v[156:159], v[140:143], v[128:131]
	v_mfma_f32_16x16x32_bf16 v[136:139], v[160:163], v[140:143], v[8:11]
	v_mfma_f32_16x16x32_bf16 v[16:19], v[148:151], v[144:147], v[16:19]
	v_mfma_f32_16x16x32_bf16 v[140:143], v[152:155], v[144:147], v[20:23]
	v_mfma_f32_16x16x32_bf16 v[148:151], v[156:159], v[144:147], v[24:27]
	v_mfma_f32_16x16x32_bf16 v[144:147], v[160:163], v[144:147], v[12:15]
	ds_read_b128 v[8:11], v118 offset:16384
	ds_read_b128 v[20:23], v118 offset:18432
	ds_read_b128 v[152:155], v118 offset:20480
	ds_read_b128 v[156:159], v118 offset:22528
	ds_read_b128 v[160:163], v119 offset:49152
	ds_read_b128 v[168:171], v119 offset:51200
	ds_read_b128 v[172:175], v119 offset:53248
	ds_read_b128 v[178:181], v119 offset:55296
	s_waitcnt lgkmcnt(3)
	v_mfma_f32_16x16x32_bf16 v[182:185], v[160:163], v[8:11], v[32:35]
	s_waitcnt lgkmcnt(2)
	v_mfma_f32_16x16x32_bf16 v[44:47], v[168:171], v[8:11], v[36:39]
	s_waitcnt lgkmcnt(1)
	v_mfma_f32_16x16x32_bf16 v[28:31], v[172:175], v[8:11], v[40:43]
	s_waitcnt lgkmcnt(0)
	v_mfma_f32_16x16x32_bf16 v[12:15], v[178:181], v[8:11], v[0:3]
	v_mfma_f32_16x16x32_bf16 v[8:11], v[178:181], v[20:23], v[4:7]
	v_mfma_f32_16x16x32_bf16 v[4:7], v[178:181], v[152:155], v[136:139]
	s_nop 2
	global_load_dwordx4 v[136:139], v[70:71], off
	v_mfma_f32_16x16x32_bf16 v[24:27], v[172:175], v[20:23], v[48:51]
	v_mfma_f32_16x16x32_bf16 v[48:51], v[160:163], v[152:155], v[96:99]
	v_mfma_f32_16x16x32_bf16 v[132:135], v[160:163], v[20:23], v[132:135]
	s_waitcnt vmcnt(0)
	s_nop 0
	v_add_f32_e32 v97, v183, v137
	s_nop 3
	v_add_f32_e32 v48, v48, v136
	v_add_f32_e32 v49, v49, v137
	v_mul_f32_e32 v48, 0xbfb8aa3b, v48
	v_mul_f32_e32 v49, 0xbfb8aa3b, v49
	v_exp_f32_e32 v48, v48
	v_exp_f32_e32 v49, v49
	v_mfma_f32_16x16x32_bf16 v[40:43], v[168:171], v[20:23], v[164:167]
	v_add_f32_e32 v96, v182, v136
	v_add_f32_e32 v48, 1.0, v48
	v_add_f32_e32 v49, 1.0, v49
	v_rcp_f32_e32 v48, v48
	v_rcp_f32_e32 v49, v49
	s_nop 1
	v_cvt_pk_bf16_f32 v99, v48, v49
	v_add_f32_e32 v48, v50, v138
	v_add_f32_e32 v49, v51, v139
	v_mul_f32_e32 v48, 0xbfb8aa3b, v48
	v_mul_f32_e32 v49, 0xbfb8aa3b, v49
	v_exp_f32_e32 v48, v48
	v_exp_f32_e32 v49, v49
	v_mfma_f32_16x16x32_bf16 v[20:23], v[172:175], v[152:155], v[128:131]
	v_mul_f32_e32 v97, 0xbfb8aa3b, v97
	v_add_f32_e32 v48, 1.0, v48
	v_add_f32_e32 v49, 1.0, v49
	v_mfma_f32_16x16x32_bf16 v[128:131], v[160:163], v[156:159], v[16:19]
	v_rcp_f32_e32 v48, v48
	v_rcp_f32_e32 v49, v49
	s_nop 1
	v_cvt_pk_bf16_f32 v98, v48, v49
	v_mfma_f32_16x16x32_bf16 v[36:39], v[168:171], v[152:155], v[100:103]
	v_mul_f32_e32 v96, 0xbfb8aa3b, v96
	s_nop 3
	v_add_f32_e32 v48, v128, v136
	v_add_f32_e32 v49, v129, v137
	v_mul_f32_e32 v48, 0xbfb8aa3b, v48
	v_mul_f32_e32 v49, 0xbfb8aa3b, v49
	v_exp_f32_e32 v48, v48
	v_exp_f32_e32 v49, v49
	v_mfma_f32_16x16x32_bf16 v[32:35], v[168:171], v[156:159], v[140:143]
	v_exp_f32_e32 v97, v97
	v_add_f32_e32 v48, 1.0, v48
	v_add_f32_e32 v49, 1.0, v49
	v_rcp_f32_e32 v48, v48
	v_rcp_f32_e32 v49, v49
	s_nop 1
	v_cvt_pk_bf16_f32 v102, v48, v49
	v_add_f32_e32 v48, v130, v138
	v_add_f32_e32 v49, v131, v139
	v_mul_f32_e32 v48, 0xbfb8aa3b, v48
	v_mul_f32_e32 v49, 0xbfb8aa3b, v49
	v_exp_f32_e32 v48, v48
	v_exp_f32_e32 v49, v49
	v_mfma_f32_16x16x32_bf16 v[0:3], v[178:181], v[156:159], v[144:147]
	v_exp_f32_e32 v96, v96
	v_add_f32_e32 v48, 1.0, v48
	v_add_f32_e32 v49, 1.0, v49
	v_rcp_f32_e32 v48, v48
	v_rcp_f32_e32 v49, v49
	s_nop 1
	v_cvt_pk_bf16_f32 v101, v48, v49
	global_load_dwordx4 v[48:51], v[70:71], off offset:64
	v_mfma_f32_16x16x32_bf16 v[16:19], v[172:175], v[156:159], v[148:151]
	v_add_f32_e32 v97, 1.0, v97
	v_add_f32_e32 v96, 1.0, v96
	v_rcp_f32_e32 v97, v97
	v_rcp_f32_e32 v96, v96
	s_nop 1
	v_cvt_pk_bf16_f32 v152, v96, v97
	v_add_f32_e32 v97, v185, v139
	v_add_f32_e32 v96, v184, v138
	v_mul_f32_e32 v97, 0xbfb8aa3b, v97
	v_mul_f32_e32 v96, 0xbfb8aa3b, v96
	v_exp_f32_e32 v97, v97
	v_exp_f32_e32 v96, v96
	v_or_b32_e32 v100, s22, v74
	v_add_f32_e32 v97, 1.0, v97
	v_add_f32_e32 v96, 1.0, v96
	v_rcp_f32_e32 v97, v97
	v_rcp_f32_e32 v96, v96
	s_nop 1
	v_cvt_pk_bf16_f32 v105, v96, v97
	v_add_f32_e32 v97, v133, v137
	v_add_f32_e32 v96, v132, v136
	v_mul_f32_e32 v97, 0xbfb8aa3b, v97
	v_mul_f32_e32 v96, 0xbfb8aa3b, v96
	v_exp_f32_e32 v97, v97
	v_exp_f32_e32 v96, v96
	v_add_f32_e32 v97, 1.0, v97
	v_add_f32_e32 v96, 1.0, v96
	v_rcp_f32_e32 v97, v97
	v_rcp_f32_e32 v96, v96
	s_nop 1
	v_cvt_pk_bf16_f32 v104, v96, v97
	v_add_f32_e32 v97, v135, v139
	v_add_f32_e32 v96, v134, v138
	v_mul_f32_e32 v96, 0xbfb8aa3b, v96
	v_exp_f32_e32 v96, v96
	v_mul_f32_e32 v97, 0xbfb8aa3b, v97
	v_exp_f32_e32 v97, v97
	v_add_f32_e32 v96, 1.0, v96
	v_rcp_f32_e32 v96, v96
	v_add_f32_e32 v97, 1.0, v97
	v_rcp_f32_e32 v97, v97
	s_nop 1
	v_cvt_pk_bf16_f32 v103, v96, v97
	s_waitcnt vmcnt(0)
	v_add_f32_e32 v32, v32, v48
	v_add_f32_e32 v33, v33, v49
	v_mul_f32_e32 v32, 0xbfb8aa3b, v32
	v_mul_f32_e32 v33, 0xbfb8aa3b, v33
	v_exp_f32_e32 v32, v32
	v_exp_f32_e32 v33, v33
	v_add_f32_e32 v44, v44, v48
	v_add_f32_e32 v45, v45, v49
	v_add_f32_e32 v32, 1.0, v32
	v_add_f32_e32 v33, 1.0, v33
	v_rcp_f32_e32 v32, v32
	v_rcp_f32_e32 v33, v33
	s_nop 1
	v_cvt_pk_bf16_f32 v145, v32, v33
	v_add_f32_e32 v32, v34, v50
	v_add_f32_e32 v33, v35, v51
	v_mul_f32_e32 v32, 0xbfb8aa3b, v32
	v_mul_f32_e32 v33, 0xbfb8aa3b, v33
	v_exp_f32_e32 v32, v32
	v_exp_f32_e32 v33, v33
	v_add_f32_e32 v40, v40, v48
	v_add_f32_e32 v41, v41, v49
	v_add_f32_e32 v32, 1.0, v32
	v_add_f32_e32 v33, 1.0, v33
	v_rcp_f32_e32 v32, v32
	v_rcp_f32_e32 v33, v33
	s_nop 1
	v_cvt_pk_bf16_f32 v144, v32, v33
	global_load_dwordx4 v[32:35], v[70:71], off offset:128
	v_add_f32_e32 v36, v36, v48
	v_add_f32_e32 v37, v37, v49
	v_mul_f32_e32 v44, 0xbfb8aa3b, v44
	v_mul_f32_e32 v45, 0xbfb8aa3b, v45
	v_mul_f32_e32 v40, 0xbfb8aa3b, v40
	v_mul_f32_e32 v41, 0xbfb8aa3b, v41
	v_mul_f32_e32 v36, 0xbfb8aa3b, v36
	v_mul_f32_e32 v37, 0xbfb8aa3b, v37
	v_exp_f32_e32 v44, v44
	v_exp_f32_e32 v45, v45
	v_exp_f32_e32 v40, v40
	v_exp_f32_e32 v41, v41
	v_exp_f32_e32 v36, v36
	v_exp_f32_e32 v37, v37
	v_add_f32_e32 v44, 1.0, v44
	v_add_f32_e32 v45, 1.0, v45
	v_add_f32_e32 v40, 1.0, v40
	v_add_f32_e32 v41, 1.0, v41
	v_add_f32_e32 v36, 1.0, v36
	v_add_f32_e32 v37, 1.0, v37
	v_rcp_f32_e32 v44, v44
	v_rcp_f32_e32 v45, v45
	v_rcp_f32_e32 v40, v40
	v_rcp_f32_e32 v41, v41
	v_rcp_f32_e32 v36, v36
	v_rcp_f32_e32 v37, v37
	s_nop 1
	v_cvt_pk_bf16_f32 v151, v44, v45
	v_add_f32_e32 v44, v46, v50
	v_add_f32_e32 v45, v47, v51
	s_nop 1
	v_cvt_pk_bf16_f32 v149, v40, v41
	v_add_f32_e32 v40, v42, v50
	v_add_f32_e32 v41, v43, v51
	s_nop 1
	v_cvt_pk_bf16_f32 v147, v36, v37
	v_add_f32_e32 v36, v38, v50
	v_add_f32_e32 v37, v39, v51
	v_mul_f32_e32 v44, 0xbfb8aa3b, v44
	v_mul_f32_e32 v45, 0xbfb8aa3b, v45
	v_mul_f32_e32 v40, 0xbfb8aa3b, v40
	v_mul_f32_e32 v41, 0xbfb8aa3b, v41
	v_mul_f32_e32 v36, 0xbfb8aa3b, v36
	v_mul_f32_e32 v37, 0xbfb8aa3b, v37
	v_exp_f32_e32 v44, v44
	v_exp_f32_e32 v45, v45
	v_exp_f32_e32 v40, v40
	v_exp_f32_e32 v41, v41
	v_exp_f32_e32 v36, v36
	v_exp_f32_e32 v37, v37
	v_add_f32_e32 v44, 1.0, v44
	v_add_f32_e32 v45, 1.0, v45
	v_add_f32_e32 v40, 1.0, v40
	v_add_f32_e32 v41, 1.0, v41
	v_add_f32_e32 v36, 1.0, v36
	v_add_f32_e32 v37, 1.0, v37
	v_rcp_f32_e32 v44, v44
	v_rcp_f32_e32 v45, v45
	v_rcp_f32_e32 v40, v40
	v_rcp_f32_e32 v41, v41
	v_rcp_f32_e32 v36, v36
	v_rcp_f32_e32 v37, v37
	s_nop 1
	v_cvt_pk_bf16_f32 v150, v44, v45
	s_nop 1
	v_cvt_pk_bf16_f32 v148, v40, v41
	s_nop 1
	v_cvt_pk_bf16_f32 v146, v36, v37
	s_waitcnt vmcnt(0)
	v_add_f32_e32 v16, v16, v32
	v_add_f32_e32 v17, v17, v33
	v_mul_f32_e32 v16, 0xbfb8aa3b, v16
	v_mul_f32_e32 v17, 0xbfb8aa3b, v17
	v_exp_f32_e32 v16, v16
	v_exp_f32_e32 v17, v17
	v_add_f32_e32 v28, v28, v32
	v_add_f32_e32 v29, v29, v33
	v_add_f32_e32 v16, 1.0, v16
	v_add_f32_e32 v17, 1.0, v17
	v_rcp_f32_e32 v16, v16
	v_rcp_f32_e32 v17, v17
	s_nop 1
	v_cvt_pk_bf16_f32 v137, v16, v17
	v_add_f32_e32 v16, v18, v34
	v_add_f32_e32 v17, v19, v35
	v_mul_f32_e32 v16, 0xbfb8aa3b, v16
	v_mul_f32_e32 v17, 0xbfb8aa3b, v17
	v_exp_f32_e32 v16, v16
	v_exp_f32_e32 v17, v17
	v_add_f32_e32 v24, v24, v32
	v_add_f32_e32 v25, v25, v33
	v_add_f32_e32 v16, 1.0, v16
	v_add_f32_e32 v17, 1.0, v17
	v_rcp_f32_e32 v16, v16
	v_rcp_f32_e32 v17, v17
	s_nop 1
	v_cvt_pk_bf16_f32 v136, v16, v17
	global_load_dwordx4 v[16:19], v[70:71], off offset:192
	s_barrier
	v_add_f32_e32 v20, v20, v32
	v_add_f32_e32 v21, v21, v33
	v_mul_f32_e32 v28, 0xbfb8aa3b, v28
	v_mul_f32_e32 v29, 0xbfb8aa3b, v29
	v_mul_f32_e32 v24, 0xbfb8aa3b, v24
	v_mul_f32_e32 v25, 0xbfb8aa3b, v25
	v_mul_f32_e32 v20, 0xbfb8aa3b, v20
	v_mul_f32_e32 v21, 0xbfb8aa3b, v21
	v_exp_f32_e32 v28, v28
	v_exp_f32_e32 v29, v29
	v_exp_f32_e32 v24, v24
	v_exp_f32_e32 v25, v25
	v_exp_f32_e32 v20, v20
	v_exp_f32_e32 v21, v21
	v_add_f32_e32 v28, 1.0, v28
	v_add_f32_e32 v29, 1.0, v29
	v_add_f32_e32 v24, 1.0, v24
	v_add_f32_e32 v25, 1.0, v25
	v_add_f32_e32 v20, 1.0, v20
	v_add_f32_e32 v21, 1.0, v21
	v_rcp_f32_e32 v28, v28
	v_rcp_f32_e32 v29, v29
	v_rcp_f32_e32 v24, v24
	v_rcp_f32_e32 v25, v25
	v_rcp_f32_e32 v20, v20
	v_rcp_f32_e32 v21, v21
	s_nop 1
	v_cvt_pk_bf16_f32 v143, v28, v29
	v_add_f32_e32 v28, v30, v34
	v_add_f32_e32 v29, v31, v35
	s_nop 1
	v_cvt_pk_bf16_f32 v141, v24, v25
	v_add_f32_e32 v24, v26, v34
	v_add_f32_e32 v25, v27, v35
	s_nop 1
	v_cvt_pk_bf16_f32 v139, v20, v21
	v_add_f32_e32 v20, v22, v34
	v_add_f32_e32 v21, v23, v35
	v_mul_f32_e32 v28, 0xbfb8aa3b, v28
	v_mul_f32_e32 v29, 0xbfb8aa3b, v29
	v_mul_f32_e32 v24, 0xbfb8aa3b, v24
	v_mul_f32_e32 v25, 0xbfb8aa3b, v25
	v_mul_f32_e32 v20, 0xbfb8aa3b, v20
	v_mul_f32_e32 v21, 0xbfb8aa3b, v21
	v_exp_f32_e32 v28, v28
	v_exp_f32_e32 v29, v29
	v_exp_f32_e32 v24, v24
	v_exp_f32_e32 v25, v25
	v_exp_f32_e32 v20, v20
	v_exp_f32_e32 v21, v21
	v_add_f32_e32 v28, 1.0, v28
	v_add_f32_e32 v29, 1.0, v29
	v_add_f32_e32 v24, 1.0, v24
	v_add_f32_e32 v25, 1.0, v25
	v_add_f32_e32 v20, 1.0, v20
	v_add_f32_e32 v21, 1.0, v21
	v_rcp_f32_e32 v28, v28
	v_rcp_f32_e32 v29, v29
	v_rcp_f32_e32 v24, v24
	v_rcp_f32_e32 v25, v25
	v_rcp_f32_e32 v20, v20
	v_rcp_f32_e32 v21, v21
	s_nop 1
	v_cvt_pk_bf16_f32 v142, v28, v29
	s_nop 1
	v_cvt_pk_bf16_f32 v140, v24, v25
	s_nop 1
	v_cvt_pk_bf16_f32 v138, v20, v21
	s_waitcnt vmcnt(0)
	v_add_f32_e32 v4, v4, v16
	v_add_f32_e32 v5, v5, v17
	v_mul_f32_e32 v4, 0xbfb8aa3b, v4
	v_mul_f32_e32 v5, 0xbfb8aa3b, v5
	v_add_f32_e32 v0, v0, v16
	v_add_f32_e32 v1, v1, v17
	v_exp_f32_e32 v4, v4
	v_exp_f32_e32 v5, v5
	v_mul_f32_e32 v0, 0xbfb8aa3b, v0
	v_mul_f32_e32 v1, 0xbfb8aa3b, v1
	v_exp_f32_e32 v0, v0
	v_exp_f32_e32 v1, v1
	v_add_f32_e32 v4, 1.0, v4
	v_add_f32_e32 v5, 1.0, v5
	v_rcp_f32_e32 v4, v4
	v_rcp_f32_e32 v5, v5
	v_add_f32_e32 v0, 1.0, v0
	v_add_f32_e32 v1, 1.0, v1
	s_nop 1
	v_cvt_pk_bf16_f32 v131, v4, v5
	v_add_f32_e32 v4, v6, v18
	v_add_f32_e32 v5, v7, v19
	v_rcp_f32_e32 v0, v0
	v_rcp_f32_e32 v1, v1
	v_mul_f32_e32 v4, 0xbfb8aa3b, v4
	v_mul_f32_e32 v5, 0xbfb8aa3b, v5
	s_nop 1
	v_cvt_pk_bf16_f32 v129, v0, v1
	v_add_f32_e32 v0, v2, v18
	v_add_f32_e32 v1, v3, v19
	v_exp_f32_e32 v4, v4
	v_exp_f32_e32 v5, v5
	v_mul_f32_e32 v0, 0xbfb8aa3b, v0
	v_mul_f32_e32 v1, 0xbfb8aa3b, v1
	v_exp_f32_e32 v0, v0
	v_exp_f32_e32 v1, v1
	v_add_f32_e32 v4, 1.0, v4
	v_add_f32_e32 v5, 1.0, v5
	v_rcp_f32_e32 v4, v4
	v_rcp_f32_e32 v5, v5
	v_add_f32_e32 v0, 1.0, v0
	v_add_f32_e32 v1, 1.0, v1
	s_nop 1
	v_cvt_pk_bf16_f32 v130, v4, v5
	v_rcp_f32_e32 v0, v0
	v_rcp_f32_e32 v1, v1
	v_lshl_add_u64 v[4:5], v[52:53], 0, s[0:1]
	s_nop 1
	v_cvt_pk_bf16_f32 v128, v0, v1
	v_lshl_add_u64 v[0:1], v[4:5], 0, v[54:55]
	global_load_dwordx4 v[0:3], v[0:1], off
	v_add_f32_e32 v12, v12, v16
	v_add_f32_e32 v13, v13, v17
	v_add_f32_e32 v8, v8, v16
	v_add_f32_e32 v9, v9, v17
	v_mul_f32_e32 v12, 0xbfb8aa3b, v12
	v_mul_f32_e32 v13, 0xbfb8aa3b, v13
	v_mul_f32_e32 v8, 0xbfb8aa3b, v8
	v_mul_f32_e32 v9, 0xbfb8aa3b, v9
	v_exp_f32_e32 v12, v12
	v_exp_f32_e32 v13, v13
	v_exp_f32_e32 v8, v8
	v_exp_f32_e32 v9, v9
	v_add_f32_e32 v12, 1.0, v12
	v_add_f32_e32 v13, 1.0, v13
	v_add_f32_e32 v8, 1.0, v8
	v_add_f32_e32 v9, 1.0, v9
	v_rcp_f32_e32 v12, v12
	v_rcp_f32_e32 v13, v13
	v_rcp_f32_e32 v8, v8
	v_rcp_f32_e32 v9, v9
	s_nop 1
	v_cvt_pk_bf16_f32 v135, v12, v13
	v_add_f32_e32 v12, v14, v18
	v_add_f32_e32 v13, v15, v19
	s_nop 1
	v_cvt_pk_bf16_f32 v133, v8, v9
	v_add_f32_e32 v8, v10, v18
	v_add_f32_e32 v9, v11, v19
	v_mul_f32_e32 v12, 0xbfb8aa3b, v12
	v_mul_f32_e32 v13, 0xbfb8aa3b, v13
	v_mul_f32_e32 v8, 0xbfb8aa3b, v8
	v_mul_f32_e32 v9, 0xbfb8aa3b, v9
	v_exp_f32_e32 v12, v12
	v_exp_f32_e32 v13, v13
	v_exp_f32_e32 v8, v8
	v_exp_f32_e32 v9, v9
	v_add_f32_e32 v12, 1.0, v12
	v_add_f32_e32 v13, 1.0, v13
	v_add_f32_e32 v8, 1.0, v8
	v_add_f32_e32 v9, 1.0, v9
	v_rcp_f32_e32 v12, v12
	v_rcp_f32_e32 v13, v13
	v_rcp_f32_e32 v8, v8
	v_rcp_f32_e32 v9, v9
	s_nop 1
	v_cvt_pk_bf16_f32 v134, v12, v13
	s_nop 1
	v_cvt_pk_bf16_f32 v132, v8, v9
	s_mov_b32 s0, 0x800000
	v_lshl_add_u64 v[8:9], v[4:5], 0, v[56:57]
	global_load_dwordx4 v[8:11], v[8:9], off
	v_lshl_add_u64 v[12:13], v[4:5], 0, v[58:59]
	global_load_dwordx4 v[12:15], v[12:13], off
	v_lshl_add_u64 v[16:17], v[4:5], 0, v[60:61]
	global_load_dwordx4 v[16:19], v[16:17], off
	v_lshl_add_u64 v[20:21], v[4:5], 0, v[62:63]
	global_load_dwordx4 v[20:23], v[20:21], off
	v_lshl_add_u64 v[24:25], v[4:5], 0, v[64:65]
	global_load_dwordx4 v[24:27], v[24:25], off
	v_lshl_add_u64 v[28:29], v[4:5], 0, v[66:67]
	global_load_dwordx4 v[28:31], v[28:29], off
	v_lshl_add_u64 v[32:33], v[4:5], 0, v[68:69]
	global_load_dwordx4 v[32:35], v[32:33], off
	s_waitcnt vmcnt(7)
	ds_write_b128 v120, v[0:3] offset:32768
	s_waitcnt vmcnt(6)
	ds_write_b128 v121, v[8:11] offset:32768
	s_waitcnt vmcnt(5)
	ds_write_b128 v122, v[12:15] offset:32768
	s_waitcnt vmcnt(4)
	ds_write_b128 v123, v[16:19] offset:32768
	s_waitcnt vmcnt(3)
	ds_write_b128 v124, v[20:23] offset:32768
	s_waitcnt vmcnt(2)
	ds_write_b128 v125, v[24:27] offset:32768
	s_waitcnt vmcnt(1)
	ds_write_b128 v126, v[28:31] offset:32768
	s_waitcnt vmcnt(0)
	ds_write_b128 v127, v[32:35] offset:32768
	s_waitcnt lgkmcnt(0)
	s_barrier
	ds_read_b128 v[0:3], v116
	ds_read_b128 v[4:7], v116 offset:2048
	ds_read_b128 v[8:11], v116 offset:4096
	ds_read_b128 v[12:15], v116 offset:6144
	ds_read_b128 v[16:19], v117 offset:32768
	ds_read_b128 v[20:23], v117 offset:34816
	ds_read_b128 v[24:27], v117 offset:36864
	ds_read_b128 v[28:31], v117 offset:38912
	s_waitcnt lgkmcnt(3)
	v_mfma_f32_16x16x32_bf16 v[32:35], v[16:19], v[0:3], 0
	s_waitcnt lgkmcnt(2)
	v_mfma_f32_16x16x32_bf16 v[36:39], v[20:23], v[0:3], 0
	s_waitcnt lgkmcnt(1)
	v_mfma_f32_16x16x32_bf16 v[40:43], v[24:27], v[0:3], 0
	s_waitcnt lgkmcnt(0)
	v_mfma_f32_16x16x32_bf16 v[0:3], v[28:31], v[0:3], 0
	v_mfma_f32_16x16x32_bf16 v[44:47], v[16:19], v[4:7], 0
	v_mfma_f32_16x16x32_bf16 v[48:51], v[20:23], v[4:7], 0
	v_mfma_f32_16x16x32_bf16 v[52:55], v[24:27], v[4:7], 0
	v_mfma_f32_16x16x32_bf16 v[4:7], v[28:31], v[4:7], 0
	v_mfma_f32_16x16x32_bf16 v[56:59], v[16:19], v[8:11], 0
	v_mfma_f32_16x16x32_bf16 v[60:63], v[20:23], v[8:11], 0
	v_mfma_f32_16x16x32_bf16 v[64:67], v[24:27], v[8:11], 0
	v_mfma_f32_16x16x32_bf16 v[8:11], v[28:31], v[8:11], 0
	v_mfma_f32_16x16x32_bf16 v[16:19], v[16:19], v[12:15], 0
	v_mfma_f32_16x16x32_bf16 v[20:23], v[20:23], v[12:15], 0
	v_mfma_f32_16x16x32_bf16 v[24:27], v[24:27], v[12:15], 0
	v_mfma_f32_16x16x32_bf16 v[12:15], v[28:31], v[12:15], 0
	ds_read_b128 v[28:31], v118
	ds_read_b128 v[68:71], v118 offset:2048
	ds_read_b128 v[154:157], v118 offset:4096
	ds_read_b128 v[158:161], v118 offset:6144
	ds_read_b128 v[162:165], v119 offset:32768
	ds_read_b128 v[166:169], v119 offset:34816
	ds_read_b128 v[170:173], v119 offset:36864
	ds_read_b128 v[178:181], v119 offset:38912
	s_waitcnt lgkmcnt(3)
	v_mfma_f32_16x16x32_bf16 v[32:35], v[162:165], v[28:31], v[32:35]
	s_waitcnt lgkmcnt(2)
	v_mfma_f32_16x16x32_bf16 v[36:39], v[166:169], v[28:31], v[36:39]
	s_waitcnt lgkmcnt(1)
	v_mfma_f32_16x16x32_bf16 v[40:43], v[170:173], v[28:31], v[40:43]
	s_waitcnt lgkmcnt(0)
	v_mfma_f32_16x16x32_bf16 v[0:3], v[178:181], v[28:31], v[0:3]
	v_mfma_f32_16x16x32_bf16 v[28:31], v[162:165], v[68:71], v[44:47]
	v_mfma_f32_16x16x32_bf16 v[44:47], v[166:169], v[68:71], v[48:51]
	v_mfma_f32_16x16x32_bf16 v[48:51], v[170:173], v[68:71], v[52:55]
	v_mfma_f32_16x16x32_bf16 v[52:55], v[162:165], v[154:157], v[56:59]
	v_mfma_f32_16x16x32_bf16 v[4:7], v[178:181], v[68:71], v[4:7]
	v_mfma_f32_16x16x32_bf16 v[56:59], v[166:169], v[154:157], v[60:63]
	v_mfma_f32_16x16x32_bf16 v[60:63], v[170:173], v[154:157], v[64:67]
	v_mfma_f32_16x16x32_bf16 v[8:11], v[178:181], v[154:157], v[8:11]
	v_mfma_f32_16x16x32_bf16 v[16:19], v[162:165], v[158:161], v[16:19]
	v_mfma_f32_16x16x32_bf16 v[20:23], v[166:169], v[158:161], v[20:23]
	v_mfma_f32_16x16x32_bf16 v[24:27], v[170:173], v[158:161], v[24:27]
	v_mfma_f32_16x16x32_bf16 v[12:15], v[178:181], v[158:161], v[12:15]
	ds_read_b128 v[64:67], v116 offset:16384
	ds_read_b128 v[68:71], v116 offset:18432
	ds_read_b128 v[154:157], v116 offset:20480
	ds_read_b128 v[158:161], v116 offset:22528
	ds_read_b128 v[162:165], v117 offset:49152
	ds_read_b128 v[166:169], v117 offset:51200
	ds_read_b128 v[170:173], v117 offset:53248
	ds_read_b128 v[178:181], v117 offset:55296
	s_waitcnt lgkmcnt(3)
	v_mfma_f32_16x16x32_bf16 v[52:55], v[162:165], v[154:157], v[52:55]
	v_mfma_f32_16x16x32_bf16 v[32:35], v[162:165], v[64:67], v[32:35]
	s_waitcnt lgkmcnt(2)
	v_mfma_f32_16x16x32_bf16 v[36:39], v[166:169], v[64:67], v[36:39]
	s_waitcnt lgkmcnt(1)
	v_mfma_f32_16x16x32_bf16 v[40:43], v[170:173], v[64:67], v[40:43]
	s_waitcnt lgkmcnt(0)
	v_mfma_f32_16x16x32_bf16 v[0:3], v[178:181], v[64:67], v[0:3]
	v_mfma_f32_16x16x32_bf16 v[182:185], v[162:165], v[68:71], v[28:31]
	v_mfma_f32_16x16x32_bf16 v[186:189], v[166:169], v[68:71], v[44:47]
	v_mfma_f32_16x16x32_bf16 v[48:51], v[170:173], v[68:71], v[48:51]
	v_mfma_f32_16x16x32_bf16 v[4:7], v[178:181], v[68:71], v[4:7]
	v_mfma_f32_16x16x32_bf16 v[68:71], v[166:169], v[154:157], v[56:59]
	v_mfma_f32_16x16x32_bf16 v[220:223], v[170:173], v[154:157], v[60:63]
	v_mfma_f32_16x16x32_bf16 v[154:157], v[178:181], v[154:157], v[8:11]
	v_mfma_f32_16x16x32_bf16 v[16:19], v[162:165], v[158:161], v[16:19]
	v_mfma_f32_16x16x32_bf16 v[162:165], v[166:169], v[158:161], v[20:23]
	v_mfma_f32_16x16x32_bf16 v[166:169], v[170:173], v[158:161], v[24:27]
	v_mfma_f32_16x16x32_bf16 v[158:161], v[178:181], v[158:161], v[12:15]
	ds_read_b128 v[8:11], v118 offset:16384
	ds_read_b128 v[20:23], v118 offset:18432
	ds_read_b128 v[170:173], v118 offset:20480
	ds_read_b128 v[178:181], v118 offset:22528
	ds_read_b128 v[224:227], v119 offset:49152
	ds_read_b128 v[228:231], v119 offset:51200
	ds_read_b128 v[232:235], v119 offset:53248
	ds_read_b128 v[236:239], v119 offset:55296
	s_waitcnt lgkmcnt(3)
	v_mfma_f32_16x16x32_bf16 v[56:59], v[224:227], v[170:173], v[52:55]
	s_nop 2
	v_or_b32_e32 v52, v100, v76
	v_ashrrev_i32_e32 v53, 31, v52
	s_waitcnt lgkmcnt(2)
	v_mfma_f32_16x16x32_bf16 v[44:47], v[228:231], v[8:11], v[36:39]
	v_mfma_f32_16x16x32_bf16 v[36:39], v[228:231], v[170:173], v[68:71]
	s_nop 2
	v_lshlrev_b64 v[68:69], 2, v[52:53]
	v_lshl_add_u64 v[52:53], s[18:19], 0, v[68:69]
	v_lshl_add_u64 v[68:69], s[20:21], 0, v[68:69]
	global_load_dwordx4 v[68:71], v[68:69], off
	v_mfma_f32_16x16x32_bf16 v[64:67], v[224:227], v[8:11], v[32:35]
	global_load_dwordx4 v[52:55], v[52:53], off
	s_waitcnt vmcnt(1)
	v_mul_f32_e32 v68, 0xbfb8aa3b, v68
	v_exp_f32_e32 v68, v68
	s_waitcnt lgkmcnt(1)
	v_mfma_f32_16x16x32_bf16 v[28:31], v[232:235], v[8:11], v[40:43]
	v_add_f32_e32 v68, 1.0, v68
	v_cmp_gt_f32_e32 vcc, s0, v68
	s_mov_b32 s0, 0x3f317217
	s_waitcnt lgkmcnt(0)
	v_mfma_f32_16x16x32_bf16 v[12:15], v[236:239], v[8:11], v[0:3]
	v_cndmask_b32_e64 v96, 0, 32, vcc
	v_ldexp_f32 v68, v68, v96
	v_log_f32_e32 v68, v68
	v_mfma_f32_16x16x32_bf16 v[8:11], v[236:239], v[20:23], v[4:7]
	v_mul_f32_e32 v96, 0x3f317217, v68
	v_fma_f32 v96, v68, s0, -v96
	v_fmac_f32_e32 v96, 0x3377d1cf, v68
	s_mov_b32 s0, 0x7f800000
	v_fmac_f32_e32 v96, 0x3f317217, v68
	v_cmp_lt_f32_e64 s[0:1], |v68|, s0
	v_mfma_f32_16x16x32_bf16 v[4:7], v[236:239], v[170:173], v[154:157]
	s_nop 0
	v_cndmask_b32_e64 v68, v68, v96, s[0:1]
	v_cndmask_b32_e32 v96, 0, v217, vcc
	v_add_u32_e32 v154, v109, v110
	v_sub_f32_e32 v68, v68, v96
	ds_read_b64 v[96:97], v154
	v_mfma_f32_16x16x32_bf16 v[60:63], v[224:227], v[20:23], v[182:185]
	v_mul_f32_e32 v153, 0xc1000000, v68
	v_lshlrev_b32_e32 v68, 16, v152
	v_mul_f32_e32 v68, v153, v68
	v_mfma_f32_16x16x32_bf16 v[40:43], v[228:231], v[20:23], v[186:189]
	v_add_f32_e32 v155, v68, v68
	s_mov_b32 s0, 0xbca3d70a
	v_cmp_nlt_f32_e32 vcc, s0, v155
	v_mfma_f32_16x16x32_bf16 v[24:27], v[232:235], v[20:23], v[48:51]
	v_mfma_f32_16x16x32_bf16 v[20:23], v[232:235], v[170:173], v[220:223]
	v_mfma_f32_16x16x32_bf16 v[48:51], v[224:227], v[178:181], v[16:19]
	v_mfma_f32_16x16x32_bf16 v[32:35], v[228:231], v[178:181], v[162:165]
	v_mfma_f32_16x16x32_bf16 v[16:19], v[232:235], v[178:181], v[166:169]
	v_mfma_f32_16x16x32_bf16 v[0:3], v[236:239], v[178:181], v[158:161]
	s_mov_b32 s2, 0x3e2aaaab
	v_mul_f32_e32 v240, 0x3fb8aa3b, v155
	v_exp_f32_e32 v240, v240
	v_fma_f32 v241, v155, s2, 0.5
	v_fma_f32 v241, v155, v241, 1.0
	v_sub_f32_e32 v240, 1.0, v240
	v_mul_f32_e64 v241, v241, -v155
	v_cndmask_b32_e32 v157, v241, v240, vcc
	v_mul_f32_e32 v69, 0xbfb8aa3b, v69
	v_exp_f32_e32 v69, v69
	s_mov_b32 s0, 0x800000
	v_add_f32_e32 v69, 1.0, v69
	v_cmp_gt_f32_e32 vcc, s0, v69
	s_mov_b32 s0, 0x3f317217
	s_nop 0
	v_cndmask_b32_e64 v155, 0, 32, vcc
	v_ldexp_f32 v69, v69, v155
	v_log_f32_e32 v69, v69
	v_cndmask_b32_e32 v155, 0, v217, vcc
	v_mul_f32_e32 v156, 0x3f317217, v69
	v_fma_f32 v156, v69, s0, -v156
	v_fmac_f32_e32 v156, 0x3377d1cf, v69
	s_mov_b32 s0, 0x7f800000
	v_fmac_f32_e32 v156, 0x3f317217, v69
	v_cmp_lt_f32_e64 vcc, |v69|, s0
	s_mov_b32 s0, 0xbca3d70a
	s_nop 0
	v_cndmask_b32_e32 v69, v69, v156, vcc
	v_sub_f32_e32 v69, v69, v155
	v_mul_f32_e32 v155, 0xc1000000, v69
	v_and_b32_e32 v69, 0xffff0000, v152
	v_mul_f32_e32 v69, v155, v69
	v_add_f32_e32 v152, v69, v69
	v_cmp_nlt_f32_e32 vcc, s0, v152
	s_mov_b32 s2, 0x3e2aaaab
	v_mul_f32_e32 v240, 0x3fb8aa3b, v152
	v_exp_f32_e32 v240, v240
	v_fma_f32 v241, v152, s2, 0.5
	v_fma_f32 v241, v152, v241, 1.0
	v_sub_f32_e32 v240, 1.0, v240
	v_mul_f32_e64 v241, v241, -v152
	v_cndmask_b32_e32 v158, v241, v240, vcc
	v_mul_f32_e32 v70, 0xbfb8aa3b, v70
	v_exp_f32_e32 v70, v70
	s_mov_b32 s0, 0x800000
	v_add_f32_e32 v70, 1.0, v70
	v_cmp_gt_f32_e32 vcc, s0, v70
	s_mov_b32 s0, 0x3f317217
	s_nop 0
	v_cndmask_b32_e64 v152, 0, 32, vcc
	v_ldexp_f32 v70, v70, v152
	v_log_f32_e32 v70, v70
	v_cndmask_b32_e32 v152, 0, v217, vcc
	v_mul_f32_e32 v156, 0x3f317217, v70
	v_fma_f32 v156, v70, s0, -v156
	v_fmac_f32_e32 v156, 0x3377d1cf, v70
	s_mov_b32 s0, 0x7f800000
	v_fmac_f32_e32 v156, 0x3f317217, v70
	v_cmp_lt_f32_e64 vcc, |v70|, s0
	s_mov_b32 s0, 0xbca3d70a
	s_nop 0
	v_cndmask_b32_e32 v70, v70, v156, vcc
	v_sub_f32_e32 v70, v70, v152
	v_mul_f32_e32 v152, 0xc1000000, v70
	v_lshlrev_b32_e32 v70, 16, v105
	v_mul_f32_e32 v70, v152, v70
	v_add_f32_e32 v156, v70, v70
	v_cmp_nlt_f32_e32 vcc, s0, v156
	s_mov_b32 s2, 0x3e2aaaab
	v_mul_f32_e32 v240, 0x3fb8aa3b, v156
	v_exp_f32_e32 v240, v240
	v_fma_f32 v241, v156, s2, 0.5
	v_fma_f32 v241, v156, v241, 1.0
	v_sub_f32_e32 v240, 1.0, v240
	v_mul_f32_e64 v241, v241, -v156
	v_cndmask_b32_e32 v159, v241, v240, vcc
	v_mul_f32_e32 v71, 0xbfb8aa3b, v71
	v_exp_f32_e32 v71, v71
	s_mov_b32 s0, 0x800000
	v_add_f32_e32 v71, 1.0, v71
	v_cmp_gt_f32_e32 vcc, s0, v71
	s_mov_b32 s0, 0x3f317217
	s_nop 0
	v_cndmask_b32_e64 v156, 0, 32, vcc
	v_ldexp_f32 v71, v71, v156
	v_log_f32_e32 v71, v71
	v_cndmask_b32_e32 v156, 0, v217, vcc
	v_mul_f32_e32 v160, 0x3f317217, v71
	v_fma_f32 v160, v71, s0, -v160
	v_fmac_f32_e32 v160, 0x3377d1cf, v71
	s_mov_b32 s0, 0x7f800000
	v_fmac_f32_e32 v160, 0x3f317217, v71
	v_cmp_lt_f32_e64 vcc, |v71|, s0
	s_mov_b32 s0, 0xbca3d70a
	s_nop 0
	v_cndmask_b32_e32 v71, v71, v160, vcc
	v_sub_f32_e32 v71, v71, v156
	v_mul_f32_e32 v156, 0xc1000000, v71
	v_and_b32_e32 v71, 0xffff0000, v105
	v_mul_f32_e32 v71, v156, v71
	v_add_f32_e32 v160, v71, v71
	v_cmp_nlt_f32_e32 vcc, s0, v160
	s_mov_b32 s2, 0x3e2aaaab
	v_mul_f32_e32 v240, 0x3fb8aa3b, v160
	v_exp_f32_e32 v240, v240
	v_fma_f32 v241, v160, s2, 0.5
	v_fma_f32 v241, v160, v241, 1.0
	v_sub_f32_e32 v240, 1.0, v240
	v_mul_f32_e64 v241, v241, -v160
	v_cndmask_b32_e32 v105, v241, v240, vcc
	s_waitcnt vmcnt(0)
	v_add_f32_e32 v66, v66, v54
	v_mul_f32_e32 v66, 0xbfb8aa3b, v66
	v_add_f32_e32 v65, v65, v53
	v_exp_f32_e32 v66, v66
	v_mul_f32_e32 v65, 0xbfb8aa3b, v65
	v_exp_f32_e32 v65, v65
	v_max_f32_e32 v159, v159, v159
	v_max_f32_e32 v159, 0, v159
	v_add_f32_e32 v66, 1.0, v66
	v_add_f32_e32 v67, v67, v55
	v_max_f32_e32 v158, v158, v158
	v_sqrt_f32_e32 v159, v159
	v_rcp_f32_e32 v66, v66
	v_mul_f32_e32 v67, 0xbfb8aa3b, v67
	v_add_f32_e32 v65, 1.0, v65
	v_max_f32_e32 v158, 0, v158
	v_exp_f32_e32 v67, v67
	v_rcp_f32_e32 v65, v65
	v_sqrt_f32_e32 v158, v158
	v_add_f32_e32 v64, v64, v52
	v_mul_f32_e32 v64, 0xbfb8aa3b, v64
	v_exp_f32_e32 v64, v64
	s_waitcnt lgkmcnt(0)
	v_lshlrev_b32_e32 v160, 16, v97
	v_mul_f32_e32 v66, v66, v159
	v_mul_f32_e32 v159, v66, v160
	v_add_f32_e32 v66, 1.0, v67
	v_and_b32_e32 v67, 0xffff0000, v96
	v_mul_f32_e32 v65, v65, v158
	v_mul_f32_e32 v65, v65, v67
	v_lshlrev_b32_e32 v67, 16, v96
	v_max_f32_e32 v96, v157, v157
	v_add_f32_e32 v64, 1.0, v64
	v_max_f32_e32 v96, 0, v96
	v_max_f32_e32 v105, v105, v105
	v_rcp_f32_e32 v64, v64
	v_sqrt_f32_e32 v96, v96
	v_max_f32_e32 v105, 0, v105
	v_rcp_f32_e32 v66, v66
	v_sqrt_f32_e32 v105, v105
	v_mul_f32_e32 v64, v64, v96
	v_mul_f32_e32 v64, v64, v67
	v_and_b32_e32 v67, 0xffff0000, v97
	v_mul_f32_e32 v66, v66, v105
	v_mul_f32_e32 v96, v66, v67
	s_nop 1
	v_cvt_pk_bf16_f32 v66, v68, v69
	v_add_u32_e32 v68, v109, v112
	ds_read_b64 v[68:69], v68
	s_nop 1
	v_cvt_pk_bf16_f32 v67, v70, v71
	v_lshlrev_b32_e32 v70, 16, v104
	v_mul_f32_e32 v70, v153, v70
	s_nop 1
	v_cvt_pk_bf16_f32 v64, v64, v65
	s_nop 1
	v_cvt_pk_bf16_f32 v65, v159, v96
	v_add_f32_e32 v96, v70, v70
	s_mov_b32 s0, 0xbca3d70a
	v_cmp_nlt_f32_e32 vcc, s0, v96
	s_mov_b32 s2, 0x3e2aaaab
	v_mul_f32_e32 v240, 0x3fb8aa3b, v96
	v_exp_f32_e32 v240, v240
	v_fma_f32 v241, v96, s2, 0.5
	v_fma_f32 v241, v96, v241, 1.0
	v_sub_f32_e32 v240, 1.0, v240
	v_mul_f32_e64 v241, v241, -v96
	v_cndmask_b32_e32 v71, v241, v240, vcc
	v_and_b32_e32 v96, 0xffff0000, v104
	v_mul_f32_e32 v96, v155, v96
	v_add_f32_e32 v97, v96, v96
	s_mov_b32 s0, 0xbca3d70a
	v_cmp_nlt_f32_e32 vcc, s0, v97
	s_mov_b32 s2, 0x3e2aaaab
	v_mul_f32_e32 v240, 0x3fb8aa3b, v97
	v_exp_f32_e32 v240, v240
	v_fma_f32 v241, v97, s2, 0.5
	v_fma_f32 v241, v97, v241, 1.0
	v_sub_f32_e32 v240, 1.0, v240
	v_mul_f32_e64 v241, v241, -v97
	v_cndmask_b32_e32 v104, v241, v240, vcc
	v_lshlrev_b32_e32 v97, 16, v103
	v_mul_f32_e32 v105, v152, v97
	v_add_f32_e32 v97, v105, v105
	s_mov_b32 s0, 0xbca3d70a
	v_cmp_nlt_f32_e32 vcc, s0, v97
	s_mov_b32 s2, 0x3e2aaaab
	v_mul_f32_e32 v240, 0x3fb8aa3b, v97
	v_exp_f32_e32 v240, v240
	v_fma_f32 v241, v97, s2, 0.5
	v_fma_f32 v241, v97, v241, 1.0
	v_sub_f32_e32 v240, 1.0, v240
	v_mul_f32_e64 v241, v241, -v97
	v_cndmask_b32_e32 v157, v241, v240, vcc
	v_and_b32_e32 v97, 0xffff0000, v103
	v_mul_f32_e32 v97, v156, v97
	v_add_f32_e32 v158, v97, v97
	s_mov_b32 s0, 0xbca3d70a
	v_cmp_nlt_f32_e32 vcc, s0, v158
	s_mov_b32 s2, 0x3e2aaaab
	v_mul_f32_e32 v240, 0x3fb8aa3b, v158
	v_exp_f32_e32 v240, v240
	v_fma_f32 v241, v158, s2, 0.5
	v_fma_f32 v241, v158, v241, 1.0
	v_sub_f32_e32 v240, 1.0, v240
	v_mul_f32_e64 v241, v241, -v158
	v_cndmask_b32_e32 v103, v241, v240, vcc
	v_add_f32_e32 v62, v62, v54
	v_add_f32_e32 v60, v60, v52
	v_mul_f32_e32 v62, 0xbfb8aa3b, v62
	v_mul_f32_e32 v60, 0xbfb8aa3b, v60
	v_exp_f32_e32 v62, v62
	v_exp_f32_e32 v60, v60
	v_max_f32_e32 v157, v157, v157
	v_max_f32_e32 v71, v71, v71
	v_add_f32_e32 v62, 1.0, v62
	v_max_f32_e32 v157, 0, v157
	v_add_f32_e32 v61, v61, v53
	v_add_f32_e32 v60, 1.0, v60
	v_max_f32_e32 v71, 0, v71
	v_rcp_f32_e32 v62, v62
	v_sqrt_f32_e32 v157, v157
	v_add_f32_e32 v63, v63, v55
	v_mul_f32_e32 v61, 0xbfb8aa3b, v61
	v_rcp_f32_e32 v60, v60
	v_sqrt_f32_e32 v71, v71
	v_mul_f32_e32 v63, 0xbfb8aa3b, v63
	v_exp_f32_e32 v61, v61
	v_exp_f32_e32 v63, v63
	v_add_u32_e32 v158, s31, v111
	s_movk_i32 s0, 0x2010
	v_cmp_eq_u32_e32 vcc, s0, v158
	v_mul_f32_e32 v62, v62, v157
	s_waitcnt lgkmcnt(0)
	v_and_b32_e32 v157, 0xffff0000, v68
	v_max_f32_e32 v104, v104, v104
	v_lshlrev_b32_e32 v68, 16, v68
	v_mul_f32_e32 v60, v60, v71
	v_add_f32_e32 v61, 1.0, v61
	v_max_f32_e32 v104, 0, v104
	v_mul_f32_e32 v60, v60, v68
	v_cndmask_b32_e32 v68, v70, v218, vcc
	v_max_f32_e32 v70, v103, v103
	v_add_f32_e32 v63, 1.0, v63
	v_rcp_f32_e32 v61, v61
	v_sqrt_f32_e32 v104, v104
	v_max_f32_e32 v70, 0, v70
	v_rcp_f32_e32 v63, v63
	v_sqrt_f32_e32 v70, v70
	v_mul_f32_e32 v61, v61, v104
	v_lshlrev_b32_e32 v158, 16, v69
	v_mul_f32_e32 v61, v61, v157
	v_cndmask_b32_e32 v96, v96, v218, vcc
	v_and_b32_e32 v69, 0xffff0000, v69
	v_mul_f32_e32 v63, v63, v70
	v_mul_f32_e32 v62, v62, v158
	v_mul_f32_e32 v63, v63, v69
	v_cndmask_b32_e32 v69, v97, v218, vcc
	s_nop 1
	v_cvt_pk_bf16_f32 v96, v68, v96
	s_nop 1
	v_cvt_pk_bf16_f32 v68, v60, v61
	ds_read_b64 v[60:61], v154 offset:4096
	v_cndmask_b32_e32 v105, v105, v218, vcc
	s_nop 1
	v_cvt_pk_bf16_f32 v97, v105, v69
	s_nop 1
	v_cvt_pk_bf16_f32 v69, v62, v63
	v_lshlrev_b32_e32 v62, 16, v99
	v_mul_f32_e32 v62, v153, v62
	v_add_f32_e32 v70, v62, v62
	s_mov_b32 s0, 0xbca3d70a
	v_cmp_nlt_f32_e64 s[0:1], s0, v70
	s_mov_b32 s2, 0x3e2aaaab
	v_mul_f32_e32 v240, 0x3fb8aa3b, v70
	v_exp_f32_e32 v240, v240
	v_fma_f32 v241, v70, s2, 0.5
	v_fma_f32 v241, v70, v241, 1.0
	v_sub_f32_e32 v240, 1.0, v240
	v_mul_f32_e64 v241, v241, -v70
	v_cndmask_b32_e64 v63, v241, v240, s[0:1]
	v_and_b32_e32 v70, 0xffff0000, v99
	v_mul_f32_e32 v70, v155, v70
	v_add_f32_e32 v71, v70, v70
	s_mov_b32 s0, 0xbca3d70a
	v_cmp_nlt_f32_e64 s[0:1], s0, v71
	s_mov_b32 s2, 0x3e2aaaab
	v_mul_f32_e32 v240, 0x3fb8aa3b, v71
	v_exp_f32_e32 v240, v240
	v_fma_f32 v241, v71, s2, 0.5
	v_fma_f32 v241, v71, v241, 1.0
	v_sub_f32_e32 v240, 1.0, v240
	v_mul_f32_e64 v241, v241, -v71
	v_cndmask_b32_e64 v99, v241, v240, s[0:1]
	v_lshlrev_b32_e32 v71, 16, v98
	v_mul_f32_e32 v71, v152, v71
	v_add_f32_e32 v103, v71, v71
	s_mov_b32 s0, 0xbca3d70a
	v_cmp_nlt_f32_e64 s[0:1], s0, v103
	s_mov_b32 s2, 0x3e2aaaab
	v_mul_f32_e32 v240, 0x3fb8aa3b, v103
	v_exp_f32_e32 v240, v240
	v_fma_f32 v241, v103, s2, 0.5
	v_fma_f32 v241, v103, v241, 1.0
	v_sub_f32_e32 v240, 1.0, v240
	v_mul_f32_e64 v241, v241, -v103
	v_cndmask_b32_e64 v104, v241, v240, s[0:1]
	v_and_b32_e32 v98, 0xffff0000, v98
	v_mul_f32_e32 v103, v156, v98
	v_add_f32_e32 v105, v103, v103
	s_mov_b32 s0, 0xbca3d70a
	v_cmp_nlt_f32_e64 s[0:1], s0, v105
	s_mov_b32 s2, 0x3e2aaaab
	v_mul_f32_e32 v240, 0x3fb8aa3b, v105
	v_exp_f32_e32 v240, v240
	v_fma_f32 v241, v105, s2, 0.5
	v_fma_f32 v241, v105, v241, 1.0
	v_sub_f32_e32 v240, 1.0, v240
	v_mul_f32_e64 v241, v241, -v105
	v_cndmask_b32_e64 v98, v241, v240, s[0:1]
	v_add_f32_e32 v58, v58, v54
	v_add_f32_e32 v57, v57, v53
	v_add_f32_e32 v56, v56, v52
	v_mul_f32_e32 v58, 0xbfb8aa3b, v58
	v_mul_f32_e32 v57, 0xbfb8aa3b, v57
	v_mul_f32_e32 v56, 0xbfb8aa3b, v56
	v_exp_f32_e32 v58, v58
	v_add_f32_e32 v59, v59, v55
	v_exp_f32_e32 v57, v57
	v_exp_f32_e32 v56, v56
	v_mul_f32_e32 v59, 0xbfb8aa3b, v59
	v_exp_f32_e32 v59, v59
	v_max_f32_e32 v104, v104, v104
	v_max_f32_e32 v99, v99, v99
	v_max_f32_e32 v63, v63, v63
	v_max_f32_e32 v104, 0, v104
	v_add_f32_e32 v58, 1.0, v58
	v_add_f32_e32 v57, 1.0, v57
	v_max_f32_e32 v99, 0, v99
	v_add_f32_e32 v56, 1.0, v56
	v_max_f32_e32 v63, 0, v63
	v_sqrt_f32_e32 v104, v104
	v_rcp_f32_e32 v58, v58
	v_rcp_f32_e32 v57, v57
	v_sqrt_f32_e32 v99, v99
	v_rcp_f32_e32 v56, v56
	v_sqrt_f32_e32 v63, v63
	v_max_f32_e32 v98, v98, v98
	v_add_f32_e32 v59, 1.0, v59
	v_max_f32_e32 v98, 0, v98
	v_rcp_f32_e32 v59, v59
	v_sqrt_f32_e32 v98, v98
	s_waitcnt lgkmcnt(0)
	v_lshlrev_b32_e32 v105, 16, v61
	v_mul_f32_e32 v58, v58, v104
	v_and_b32_e32 v104, 0xffff0000, v60
	v_mul_f32_e32 v57, v57, v99
	v_lshlrev_b32_e32 v60, 16, v60
	v_mul_f32_e32 v56, v56, v63
	v_mul_f32_e32 v58, v58, v105
	v_mul_f32_e32 v57, v57, v104
	v_mul_f32_e32 v56, v56, v60
	ds_read_b64 v[104:105], v154 offset:6144
	v_mul_f32_e32 v59, v59, v98
	s_nop 1
	v_cvt_pk_bf16_f32 v98, v62, v70
	s_nop 1
	v_cvt_pk_bf16_f32 v70, v56, v57
	v_lshlrev_b32_e32 v56, 16, v102
	v_mul_f32_e32 v153, v153, v56
	v_add_f32_e32 v56, v153, v153
	s_mov_b32 s0, 0xbca3d70a
	v_and_b32_e32 v60, 0xffff0000, v61
	v_cmp_nlt_f32_e64 s[0:1], s0, v56
	v_mul_f32_e32 v59, v59, v60
	s_nop 1
	v_cvt_pk_bf16_f32 v99, v71, v103
	s_nop 1
	v_cvt_pk_bf16_f32 v71, v58, v59
	s_mov_b32 s2, 0x3e2aaaab
	v_mul_f32_e32 v240, 0x3fb8aa3b, v56
	v_exp_f32_e32 v240, v240
	v_fma_f32 v241, v56, s2, 0.5
	v_fma_f32 v241, v56, v241, 1.0
	v_sub_f32_e32 v240, 1.0, v240
	v_mul_f32_e64 v241, v241, -v56
	v_cndmask_b32_e64 v154, v241, v240, s[0:1]
	v_and_b32_e32 v56, 0xffff0000, v102
	v_mul_f32_e32 v155, v155, v56
	v_add_f32_e32 v56, v155, v155
	s_mov_b32 s0, 0xbca3d70a
	v_cmp_nlt_f32_e64 s[0:1], s0, v56
	s_mov_b32 s2, 0x3e2aaaab
	v_mul_f32_e32 v240, 0x3fb8aa3b, v56
	v_exp_f32_e32 v240, v240
	v_fma_f32 v241, v56, s2, 0.5
	v_fma_f32 v241, v56, v241, 1.0
	v_sub_f32_e32 v240, 1.0, v240
	v_mul_f32_e64 v241, v241, -v56
	v_cndmask_b32_e64 v157, v241, v240, s[0:1]
	v_lshlrev_b32_e32 v56, 16, v101
	v_mul_f32_e32 v152, v152, v56
	v_add_f32_e32 v56, v152, v152
	s_mov_b32 s0, 0xbca3d70a
	v_cmp_nlt_f32_e64 s[0:1], s0, v56
	s_mov_b32 s2, 0x3e2aaaab
	v_mul_f32_e32 v240, 0x3fb8aa3b, v56
	v_exp_f32_e32 v240, v240
	v_fma_f32 v241, v56, s2, 0.5
	v_fma_f32 v241, v56, v241, 1.0
	v_sub_f32_e32 v240, 1.0, v240
	v_mul_f32_e64 v241, v241, -v56
	v_cndmask_b32_e64 v158, v241, v240, s[0:1]
	v_and_b32_e32 v56, 0xffff0000, v101
	v_mul_f32_e32 v156, v156, v56
	v_add_f32_e32 v56, v156, v156
	s_mov_b32 s0, 0xbca3d70a
	v_cmp_nlt_f32_e64 s[0:1], s0, v56
	s_mov_b32 s2, 0x3e2aaaab
	v_mul_f32_e32 v240, 0x3fb8aa3b, v56
	v_exp_f32_e32 v240, v240
	v_fma_f32 v241, v56, s2, 0.5
	v_fma_f32 v241, v56, v241, 1.0
	v_sub_f32_e32 v240, 1.0, v240
	v_mul_f32_e64 v241, v241, -v56
	v_cndmask_b32_e64 v159, v241, v240, s[0:1]
	v_ashrrev_i32_e32 v101, 31, v100
	v_lshl_add_u64 v[56:57], v[100:101], 0, v[76:77]
	v_lshlrev_b64 v[56:57], 2, v[56:57]
	v_lshl_add_u64 v[100:101], s[20:21], 0, v[56:57]
	global_load_dwordx4 v[60:63], v[100:101], off offset:64
	v_lshl_add_u64 v[102:103], s[18:19], 0, v[56:57]
	global_load_dwordx4 v[56:59], v[102:103], off offset:64
	v_add_f32_e32 v55, v51, v55
	v_mul_f32_e32 v55, 0xbfb8aa3b, v55
	v_exp_f32_e32 v55, v55
	v_add_f32_e32 v54, v50, v54
	v_add_f32_e32 v49, v49, v53
	v_add_f32_e32 v48, v48, v52
	v_max_f32_e32 v52, v154, v154
	v_max_f32_e32 v154, v159, v159
	v_mul_f32_e32 v54, 0xbfb8aa3b, v54
	v_mul_f32_e32 v49, 0xbfb8aa3b, v49
	v_mul_f32_e32 v48, 0xbfb8aa3b, v48
	v_max_f32_e32 v154, 0, v154
	v_add_f32_e32 v55, 1.0, v55
	v_exp_f32_e32 v54, v54
	v_exp_f32_e32 v49, v49
	v_exp_f32_e32 v48, v48
	v_sqrt_f32_e32 v154, v154
	v_rcp_f32_e32 v55, v55
	v_max_f32_e32 v158, v158, v158
	v_max_f32_e32 v53, v157, v157
	s_mov_b32 s0, 0x800000
	s_waitcnt lgkmcnt(0)
	v_lshlrev_b32_e32 v160, 16, v105
	v_and_b32_e32 v105, 0xffff0000, v105
	s_nop 1
	v_cvt_pk_bf16_f32 v50, v153, v155
	s_nop 1
	v_cvt_pk_bf16_f32 v51, v152, v156
	v_max_f32_e32 v152, 0, v158
	v_max_f32_e32 v153, 0, v53
	v_max_f32_e32 v155, 0, v52
	v_add_f32_e32 v54, 1.0, v54
	v_add_f32_e32 v49, 1.0, v49
	v_add_f32_e32 v48, 1.0, v48
	v_mul_f32_e32 v55, v55, v154
	v_sqrt_f32_e32 v152, v152
	v_sqrt_f32_e32 v153, v153
	v_sqrt_f32_e32 v155, v155
	v_rcp_f32_e32 v54, v54
	v_rcp_f32_e32 v49, v49
	v_rcp_f32_e32 v48, v48
	v_mul_f32_e32 v55, v55, v105
	v_and_b32_e32 v161, 0xffff0000, v104
	v_lshlrev_b32_e32 v157, 16, v104
	v_mul_f32_e32 v54, v54, v152
	v_mul_f32_e32 v49, v49, v153
	v_mul_f32_e32 v48, v48, v155
	v_mul_f32_e32 v54, v54, v160
	v_mul_f32_e32 v49, v49, v161
	v_mul_f32_e32 v48, v48, v157
	s_nop 1
	v_cvt_pk_bf16_f32 v48, v48, v49
	s_nop 1
	v_cvt_pk_bf16_f32 v49, v54, v55
	v_add_u32_e32 v104, v113, v110
	ds_read_b64 v[52:53], v104
	s_waitcnt vmcnt(1)
	v_mul_f32_e32 v60, 0xbfb8aa3b, v60
	v_exp_f32_e32 v60, v60
	s_nop 0
	v_add_f32_e32 v60, 1.0, v60
	v_cmp_gt_f32_e64 s[0:1], s0, v60
	s_nop 1
	v_cndmask_b32_e64 v105, 0, 32, s[0:1]
	v_ldexp_f32 v60, v60, v105
	v_log_f32_e32 v60, v60
	v_cndmask_b32_e64 v54, 0, v217, s[0:1]
	s_mov_b32 s0, 0x3f317217
	v_mul_f32_e32 v55, 0x3f317217, v60
	v_fma_f32 v55, v60, s0, -v55
	v_fmac_f32_e32 v55, 0x3377d1cf, v60
	s_mov_b32 s0, 0x7f800000
	v_fmac_f32_e32 v55, 0x3f317217, v60
	v_cmp_lt_f32_e64 s[0:1], |v60|, s0
	s_nop 1
	v_cndmask_b32_e64 v55, v60, v55, s[0:1]
	v_sub_f32_e32 v54, v55, v54
	v_mul_f32_e32 v152, 0xc1000000, v54
	v_lshlrev_b32_e32 v54, 16, v151
	v_mul_f32_e32 v54, v152, v54
	v_add_f32_e32 v60, v54, v54
	s_mov_b32 s0, 0xbca3d70a
	v_cmp_nlt_f32_e64 s[0:1], s0, v60
	s_mov_b32 s2, 0x3e2aaaab
	v_mul_f32_e32 v240, 0x3fb8aa3b, v60
	v_exp_f32_e32 v240, v240
	v_fma_f32 v241, v60, s2, 0.5
	v_fma_f32 v241, v60, v241, 1.0
	v_sub_f32_e32 v240, 1.0, v240
	v_mul_f32_e64 v241, v241, -v60
	v_cndmask_b32_e64 v55, v241, v240, s[0:1]
	v_mul_f32_e32 v60, 0xbfb8aa3b, v61
	v_exp_f32_e32 v60, v60
	s_mov_b32 s0, 0x800000
	v_add_f32_e32 v60, 1.0, v60
	v_cmp_gt_f32_e64 s[0:1], s0, v60
	s_nop 1
	v_cndmask_b32_e64 v61, 0, 32, s[0:1]
	v_ldexp_f32 v60, v60, v61
	v_log_f32_e32 v60, v60
	v_cndmask_b32_e64 v61, 0, v217, s[0:1]
	s_mov_b32 s0, 0x3f317217
	v_mul_f32_e32 v105, 0x3f317217, v60
	v_fma_f32 v105, v60, s0, -v105
	v_fmac_f32_e32 v105, 0x3377d1cf, v60
	s_mov_b32 s0, 0x7f800000
	v_fmac_f32_e32 v105, 0x3f317217, v60
	v_cmp_lt_f32_e64 s[0:1], |v60|, s0
	s_nop 1
	v_cndmask_b32_e64 v60, v60, v105, s[0:1]
	v_sub_f32_e32 v60, v60, v61
	v_mul_f32_e32 v153, 0xc1000000, v60
	v_and_b32_e32 v60, 0xffff0000, v151
	v_mul_f32_e32 v60, v153, v60
	v_add_f32_e32 v105, v60, v60
	s_mov_b32 s0, 0xbca3d70a
	v_cmp_nlt_f32_e64 s[0:1], s0, v105
	s_mov_b32 s2, 0x3e2aaaab
	v_mul_f32_e32 v240, 0x3fb8aa3b, v105
	v_exp_f32_e32 v240, v240
	v_fma_f32 v241, v105, s2, 0.5
	v_fma_f32 v241, v105, v241, 1.0
	v_sub_f32_e32 v240, 1.0, v240
	v_mul_f32_e64 v241, v241, -v105
	v_cndmask_b32_e64 v61, v241, v240, s[0:1]
	v_mul_f32_e32 v62, 0xbfb8aa3b, v62
	v_exp_f32_e32 v62, v62
	s_mov_b32 s0, 0x800000
	v_add_f32_e32 v62, 1.0, v62
	v_cmp_gt_f32_e64 s[0:1], s0, v62
	s_nop 1
	v_cndmask_b32_e64 v105, 0, 32, s[0:1]
	v_ldexp_f32 v62, v62, v105
	v_log_f32_e32 v62, v62
	v_cndmask_b32_e64 v105, 0, v217, s[0:1]
	s_mov_b32 s0, 0x3f317217
	v_mul_f32_e32 v151, 0x3f317217, v62
	v_fma_f32 v151, v62, s0, -v151
	v_fmac_f32_e32 v151, 0x3377d1cf, v62
	s_mov_b32 s0, 0x7f800000
	v_fmac_f32_e32 v151, 0x3f317217, v62
	v_cmp_lt_f32_e64 s[0:1], |v62|, s0
	s_nop 1
	v_cndmask_b32_e64 v62, v62, v151, s[0:1]
	v_sub_f32_e32 v62, v62, v105
	v_mul_f32_e32 v151, 0xc1000000, v62
	v_lshlrev_b32_e32 v62, 16, v150
	v_mul_f32_e32 v62, v151, v62
	v_add_f32_e32 v154, v62, v62
	s_mov_b32 s0, 0xbca3d70a
	v_cmp_nlt_f32_e64 s[0:1], s0, v154
	s_mov_b32 s2, 0x3e2aaaab
	v_mul_f32_e32 v240, 0x3fb8aa3b, v154
	v_exp_f32_e32 v240, v240
	v_fma_f32 v241, v154, s2, 0.5
	v_fma_f32 v241, v154, v241, 1.0
	v_sub_f32_e32 v240, 1.0, v240
	v_mul_f32_e64 v241, v241, -v154
	v_cndmask_b32_e64 v105, v241, v240, s[0:1]
	v_mul_f32_e32 v63, 0xbfb8aa3b, v63
	v_exp_f32_e32 v63, v63
	s_mov_b32 s0, 0x800000
	v_add_f32_e32 v63, 1.0, v63
	v_cmp_gt_f32_e64 s[0:1], s0, v63
	s_nop 1
	v_cndmask_b32_e64 v154, 0, 32, s[0:1]
	v_ldexp_f32 v63, v63, v154
	v_log_f32_e32 v63, v63
	v_cndmask_b32_e64 v154, 0, v217, s[0:1]
	s_mov_b32 s0, 0x3f317217
	v_mul_f32_e32 v155, 0x3f317217, v63
	v_fma_f32 v155, v63, s0, -v155
	v_fmac_f32_e32 v155, 0x3377d1cf, v63
	s_mov_b32 s0, 0x7f800000
	v_fmac_f32_e32 v155, 0x3f317217, v63
	v_cmp_lt_f32_e64 s[0:1], |v63|, s0
	s_nop 1
	v_cndmask_b32_e64 v63, v63, v155, s[0:1]
	v_sub_f32_e32 v63, v63, v154
	v_mul_f32_e32 v154, 0xc1000000, v63
	v_and_b32_e32 v63, 0xffff0000, v150
	v_mul_f32_e32 v63, v154, v63
	v_add_f32_e32 v155, v63, v63
	s_mov_b32 s0, 0xbca3d70a
	v_cmp_nlt_f32_e64 s[0:1], s0, v155
	s_mov_b32 s2, 0x3e2aaaab
	v_mul_f32_e32 v240, 0x3fb8aa3b, v155
	v_exp_f32_e32 v240, v240
	v_fma_f32 v241, v155, s2, 0.5
	v_fma_f32 v241, v155, v241, 1.0
	v_sub_f32_e32 v240, 1.0, v240
	v_mul_f32_e64 v241, v241, -v155
	v_cndmask_b32_e64 v150, v241, v240, s[0:1]
	s_waitcnt vmcnt(0)
	v_add_f32_e32 v45, v45, v57
	v_mul_f32_e32 v45, 0xbfb8aa3b, v45
	v_exp_f32_e32 v45, v45
	v_add_f32_e32 v46, v46, v58
	v_max_f32_e32 v61, v61, v61
	v_add_f32_e32 v44, v44, v56
	v_mul_f32_e32 v46, 0xbfb8aa3b, v46
	v_add_f32_e32 v47, v47, v59
	v_add_f32_e32 v45, 1.0, v45
	v_max_f32_e32 v61, 0, v61
	v_mul_f32_e32 v44, 0xbfb8aa3b, v44
	v_exp_f32_e32 v46, v46
	v_mul_f32_e32 v47, 0xbfb8aa3b, v47
	v_rcp_f32_e32 v45, v45
	v_sqrt_f32_e32 v61, v61
	v_exp_f32_e32 v44, v44
	v_exp_f32_e32 v47, v47
	v_max_f32_e32 v105, v105, v105
	v_max_f32_e32 v55, v55, v55
	v_max_f32_e32 v105, 0, v105
	v_add_f32_e32 v46, 1.0, v46
	v_mul_f32_e32 v45, v45, v61
	v_add_f32_e32 v44, 1.0, v44
	v_max_f32_e32 v55, 0, v55
	v_max_f32_e32 v61, v150, v150
	v_sqrt_f32_e32 v105, v105
	v_rcp_f32_e32 v46, v46
	v_add_f32_e32 v47, 1.0, v47
	v_rcp_f32_e32 v44, v44
	v_sqrt_f32_e32 v55, v55
	v_max_f32_e32 v61, 0, v61
	v_rcp_f32_e32 v47, v47
	v_sqrt_f32_e32 v61, v61
	s_waitcnt lgkmcnt(0)
	v_lshlrev_b32_e32 v155, 16, v53
	v_mul_f32_e32 v46, v46, v105
	v_and_b32_e32 v105, 0xffff0000, v52
	v_lshlrev_b32_e32 v52, 16, v52
	v_mul_f32_e32 v44, v44, v55
	v_mul_f32_e32 v46, v46, v155
	v_mul_f32_e32 v45, v45, v105
	v_mul_f32_e32 v44, v44, v52
	v_and_b32_e32 v52, 0xffff0000, v53
	v_mul_f32_e32 v47, v47, v61
	v_mul_f32_e32 v47, v47, v52
	s_nop 1
	v_cvt_pk_bf16_f32 v44, v44, v45
	s_nop 1
	v_cvt_pk_bf16_f32 v45, v46, v47
	v_add_u32_e32 v46, v113, v112
	ds_read_b64 v[46:47], v46
	s_nop 1
	v_cvt_pk_bf16_f32 v52, v54, v60
	v_lshlrev_b32_e32 v54, 16, v149
	v_mul_f32_e32 v54, v152, v54
	v_add_f32_e32 v60, v54, v54
	s_mov_b32 s0, 0xbca3d70a
	v_cmp_nlt_f32_e64 s[0:1], s0, v60
	s_nop 1
	v_cvt_pk_bf16_f32 v53, v62, v63
	s_mov_b32 s2, 0x3e2aaaab
	v_mul_f32_e32 v240, 0x3fb8aa3b, v60
	v_exp_f32_e32 v240, v240
	v_fma_f32 v241, v60, s2, 0.5
	v_fma_f32 v241, v60, v241, 1.0
	v_sub_f32_e32 v240, 1.0, v240
	v_mul_f32_e64 v241, v241, -v60
	v_cndmask_b32_e64 v55, v241, v240, s[0:1]
	v_and_b32_e32 v60, 0xffff0000, v149
	v_mul_f32_e32 v60, v153, v60
	v_add_f32_e32 v62, v60, v60
	s_mov_b32 s0, 0xbca3d70a
	v_cmp_nlt_f32_e64 s[0:1], s0, v62
	s_mov_b32 s2, 0x3e2aaaab
	v_mul_f32_e32 v240, 0x3fb8aa3b, v62
	v_exp_f32_e32 v240, v240
	v_fma_f32 v241, v62, s2, 0.5
	v_fma_f32 v241, v62, v241, 1.0
	v_sub_f32_e32 v240, 1.0, v240
	v_mul_f32_e64 v241, v241, -v62
	v_cndmask_b32_e64 v61, v241, v240, s[0:1]
	v_lshlrev_b32_e32 v62, 16, v148
	v_mul_f32_e32 v63, v151, v62
	v_add_f32_e32 v62, v63, v63
	s_mov_b32 s0, 0xbca3d70a
	v_cmp_nlt_f32_e64 s[0:1], s0, v62
	s_mov_b32 s2, 0x3e2aaaab
	v_mul_f32_e32 v240, 0x3fb8aa3b, v62
	v_exp_f32_e32 v240, v240
	v_fma_f32 v241, v62, s2, 0.5
	v_fma_f32 v241, v62, v241, 1.0
	v_sub_f32_e32 v240, 1.0, v240
	v_mul_f32_e64 v241, v241, -v62
	v_cndmask_b32_e64 v149, v241, v240, s[0:1]
	v_and_b32_e32 v62, 0xffff0000, v148
	v_mul_f32_e32 v62, v154, v62
	v_add_f32_e32 v148, v62, v62
	s_mov_b32 s0, 0xbca3d70a
	v_cmp_nlt_f32_e64 s[0:1], s0, v148
	s_mov_b32 s2, 0x3e2aaaab
	v_mul_f32_e32 v240, 0x3fb8aa3b, v148
	v_exp_f32_e32 v240, v240
	v_fma_f32 v241, v148, s2, 0.5
	v_fma_f32 v241, v148, v241, 1.0
	v_sub_f32_e32 v240, 1.0, v240
	v_mul_f32_e64 v241, v241, -v148
	v_cndmask_b32_e64 v105, v241, v240, s[0:1]
	v_add_f32_e32 v40, v40, v56
	v_mul_f32_e32 v40, 0xbfb8aa3b, v40
	v_exp_f32_e32 v40, v40
	v_add_f32_e32 v42, v42, v58
	v_add_f32_e32 v41, v41, v57
	v_max_f32_e32 v55, v55, v55
	v_mul_f32_e32 v42, 0xbfb8aa3b, v42
	v_add_f32_e32 v43, v43, v59
	v_mul_f32_e32 v41, 0xbfb8aa3b, v41
	v_add_f32_e32 v40, 1.0, v40
	v_max_f32_e32 v55, 0, v55
	v_exp_f32_e32 v42, v42
	v_mul_f32_e32 v43, 0xbfb8aa3b, v43
	v_exp_f32_e32 v41, v41
	v_rcp_f32_e32 v40, v40
	v_sqrt_f32_e32 v55, v55
	v_exp_f32_e32 v43, v43
	v_max_f32_e32 v148, v149, v149
	v_max_f32_e32 v61, v61, v61
	v_max_f32_e32 v148, 0, v148
	v_add_f32_e32 v42, 1.0, v42
	v_add_f32_e32 v41, 1.0, v41
	v_max_f32_e32 v61, 0, v61
	v_mul_f32_e32 v40, v40, v55
	v_max_f32_e32 v55, v105, v105
	v_sqrt_f32_e32 v148, v148
	v_rcp_f32_e32 v42, v42
	v_add_f32_e32 v43, 1.0, v43
	v_rcp_f32_e32 v41, v41
	v_sqrt_f32_e32 v61, v61
	v_max_f32_e32 v55, 0, v55
	v_rcp_f32_e32 v43, v43
	v_sqrt_f32_e32 v55, v55
	v_mul_f32_e32 v42, v42, v148
	s_waitcnt lgkmcnt(0)
	v_and_b32_e32 v148, 0xffff0000, v46
	v_mul_f32_e32 v41, v41, v61
	v_lshlrev_b32_e32 v46, 16, v46
	v_lshlrev_b32_e32 v149, 16, v47
	v_mul_f32_e32 v41, v41, v148
	v_cndmask_b32_e32 v60, v60, v218, vcc
	v_mul_f32_e32 v40, v40, v46
	v_cndmask_b32_e32 v46, v54, v218, vcc
	v_and_b32_e32 v47, 0xffff0000, v47
	v_mul_f32_e32 v43, v43, v55
	v_mul_f32_e32 v42, v42, v149
	v_mul_f32_e32 v43, v43, v47
	v_cndmask_b32_e32 v47, v62, v218, vcc
	s_nop 1
	v_cvt_pk_bf16_f32 v60, v46, v60
	s_nop 1
	v_cvt_pk_bf16_f32 v46, v40, v41
	ds_read_b64 v[40:41], v104 offset:4096
	v_cndmask_b32_e32 v63, v63, v218, vcc
	s_nop 1
	v_cvt_pk_bf16_f32 v61, v63, v47
	s_nop 1
	v_cvt_pk_bf16_f32 v47, v42, v43
	v_lshlrev_b32_e32 v42, 16, v147
	v_mul_f32_e32 v42, v152, v42
	v_add_f32_e32 v54, v42, v42
	s_mov_b32 s0, 0xbca3d70a
	v_cmp_nlt_f32_e64 s[0:1], s0, v54
	s_mov_b32 s2, 0x3e2aaaab
	v_mul_f32_e32 v240, 0x3fb8aa3b, v54
	v_exp_f32_e32 v240, v240
	v_fma_f32 v241, v54, s2, 0.5
	v_fma_f32 v241, v54, v241, 1.0
	v_sub_f32_e32 v240, 1.0, v240
	v_mul_f32_e64 v241, v241, -v54
	v_cndmask_b32_e64 v43, v241, v240, s[0:1]
	v_and_b32_e32 v54, 0xffff0000, v147
	v_mul_f32_e32 v54, v153, v54
	v_add_f32_e32 v55, v54, v54
	s_mov_b32 s0, 0xbca3d70a
	v_cmp_nlt_f32_e64 s[0:1], s0, v55
	s_mov_b32 s2, 0x3e2aaaab
	v_mul_f32_e32 v240, 0x3fb8aa3b, v55
	v_exp_f32_e32 v240, v240
	v_fma_f32 v241, v55, s2, 0.5
	v_fma_f32 v241, v55, v241, 1.0
	v_sub_f32_e32 v240, 1.0, v240
	v_mul_f32_e64 v241, v241, -v55
	v_cndmask_b32_e64 v62, v241, v240, s[0:1]
	v_lshlrev_b32_e32 v55, 16, v146
	v_mul_f32_e32 v55, v151, v55
	v_add_f32_e32 v63, v55, v55
	s_mov_b32 s0, 0xbca3d70a
	v_cmp_nlt_f32_e64 s[0:1], s0, v63
	s_mov_b32 s2, 0x3e2aaaab
	v_mul_f32_e32 v240, 0x3fb8aa3b, v63
	v_exp_f32_e32 v240, v240
	v_fma_f32 v241, v63, s2, 0.5
	v_fma_f32 v241, v63, v241, 1.0
	v_sub_f32_e32 v240, 1.0, v240
	v_mul_f32_e64 v241, v241, -v63
	v_cndmask_b32_e64 v147, v241, v240, s[0:1]
	v_and_b32_e32 v63, 0xffff0000, v146
	v_mul_f32_e32 v63, v154, v63
	v_add_f32_e32 v146, v63, v63
	s_mov_b32 s0, 0xbca3d70a
	v_cmp_nlt_f32_e64 s[0:1], s0, v146
	s_mov_b32 s2, 0x3e2aaaab
	v_mul_f32_e32 v240, 0x3fb8aa3b, v146
	v_exp_f32_e32 v240, v240
	v_fma_f32 v241, v146, s2, 0.5
	v_fma_f32 v241, v146, v241, 1.0
	v_sub_f32_e32 v240, 1.0, v240
	v_mul_f32_e64 v241, v241, -v146
	v_cndmask_b32_e64 v105, v241, v240, s[0:1]
	v_add_f32_e32 v37, v37, v57
	v_mul_f32_e32 v37, 0xbfb8aa3b, v37
	v_exp_f32_e32 v37, v37
	v_add_f32_e32 v38, v38, v58
	v_add_f32_e32 v36, v36, v56
	v_mul_f32_e32 v38, 0xbfb8aa3b, v38
	v_max_f32_e32 v62, v62, v62
	v_mul_f32_e32 v36, 0xbfb8aa3b, v36
	v_exp_f32_e32 v38, v38
	v_add_f32_e32 v39, v39, v59
	v_add_f32_e32 v37, 1.0, v37
	v_max_f32_e32 v62, 0, v62
	v_exp_f32_e32 v36, v36
	v_mul_f32_e32 v39, 0xbfb8aa3b, v39
	v_rcp_f32_e32 v37, v37
	v_sqrt_f32_e32 v62, v62
	v_exp_f32_e32 v39, v39
	v_max_f32_e32 v146, v147, v147
	v_max_f32_e32 v43, v43, v43
	v_max_f32_e32 v146, 0, v146
	v_add_f32_e32 v38, 1.0, v38
	v_add_f32_e32 v36, 1.0, v36
	v_max_f32_e32 v43, 0, v43
	v_sqrt_f32_e32 v146, v146
	v_rcp_f32_e32 v38, v38
	v_mul_f32_e32 v37, v37, v62
	v_rcp_f32_e32 v36, v36
	v_sqrt_f32_e32 v43, v43
	v_max_f32_e32 v62, v105, v105
	v_add_f32_e32 v39, 1.0, v39
	v_max_f32_e32 v62, 0, v62
	v_rcp_f32_e32 v39, v39
	v_sqrt_f32_e32 v62, v62
	v_mul_f32_e32 v38, v38, v146
	s_waitcnt lgkmcnt(0)
	v_and_b32_e32 v146, 0xffff0000, v40
	v_lshlrev_b32_e32 v40, 16, v40
	v_mul_f32_e32 v36, v36, v43
	v_mul_f32_e32 v36, v36, v40
	ds_read_b64 v[104:105], v104 offset:6144
	v_mul_f32_e32 v37, v37, v146
	v_mul_f32_e32 v39, v39, v62
	s_nop 1
	v_cvt_pk_bf16_f32 v62, v42, v54
	s_nop 1
	v_cvt_pk_bf16_f32 v54, v36, v37
	v_lshlrev_b32_e32 v36, 16, v145
	v_mul_f32_e32 v146, v152, v36
	v_add_f32_e32 v36, v146, v146
	s_mov_b32 s0, 0xbca3d70a
	v_lshlrev_b32_e32 v147, 16, v41
	v_and_b32_e32 v40, 0xffff0000, v41
	v_cmp_nlt_f32_e64 s[0:1], s0, v36
	v_mul_f32_e32 v38, v38, v147
	v_mul_f32_e32 v39, v39, v40
	s_nop 1
	v_cvt_pk_bf16_f32 v63, v55, v63
	s_nop 1
	v_cvt_pk_bf16_f32 v55, v38, v39
	s_mov_b32 s2, 0x3e2aaaab
	v_mul_f32_e32 v240, 0x3fb8aa3b, v36
	v_exp_f32_e32 v240, v240
	v_fma_f32 v241, v36, s2, 0.5
	v_fma_f32 v241, v36, v241, 1.0
	v_sub_f32_e32 v240, 1.0, v240
	v_mul_f32_e64 v241, v241, -v36
	v_cndmask_b32_e64 v147, v241, v240, s[0:1]
	v_and_b32_e32 v36, 0xffff0000, v145
	v_mul_f32_e32 v145, v153, v36
	v_add_f32_e32 v36, v145, v145
	s_mov_b32 s0, 0xbca3d70a
	v_cmp_nlt_f32_e64 s[0:1], s0, v36
	s_mov_b32 s2, 0x3e2aaaab
	v_mul_f32_e32 v240, 0x3fb8aa3b, v36
	v_exp_f32_e32 v240, v240
	v_fma_f32 v241, v36, s2, 0.5
	v_fma_f32 v241, v36, v241, 1.0
	v_sub_f32_e32 v240, 1.0, v240
	v_mul_f32_e64 v241, v241, -v36
	v_cndmask_b32_e64 v148, v241, v240, s[0:1]
	v_lshlrev_b32_e32 v36, 16, v144
	v_mul_f32_e32 v149, v151, v36
	v_add_f32_e32 v36, v149, v149
	s_mov_b32 s0, 0xbca3d70a
	v_cmp_nlt_f32_e64 s[0:1], s0, v36
	s_mov_b32 s2, 0x3e2aaaab
	v_mul_f32_e32 v240, 0x3fb8aa3b, v36
	v_exp_f32_e32 v240, v240
	v_fma_f32 v241, v36, s2, 0.5
	v_fma_f32 v241, v36, v241, 1.0
	v_sub_f32_e32 v240, 1.0, v240
	v_mul_f32_e64 v241, v241, -v36
	v_cndmask_b32_e64 v150, v241, v240, s[0:1]
	v_and_b32_e32 v36, 0xffff0000, v144
	v_mul_f32_e32 v144, v154, v36
	v_add_f32_e32 v36, v144, v144
	s_mov_b32 s0, 0xbca3d70a
	v_cmp_nlt_f32_e64 s[0:1], s0, v36
	s_mov_b32 s2, 0x3e2aaaab
	v_mul_f32_e32 v240, 0x3fb8aa3b, v36
	v_exp_f32_e32 v240, v240
	v_fma_f32 v241, v36, s2, 0.5
	v_fma_f32 v241, v36, v241, 1.0
	v_sub_f32_e32 v240, 1.0, v240
	v_mul_f32_e64 v241, v241, -v36
	v_cndmask_b32_e64 v151, v241, v240, s[0:1]
	global_load_dwordx4 v[40:43], v[100:101], off offset:128
	global_load_dwordx4 v[36:39], v[102:103], off offset:128
	v_add_f32_e32 v32, v32, v56
	v_mul_f32_e32 v32, 0xbfb8aa3b, v32
	v_exp_f32_e32 v32, v32
	v_add_f32_e32 v59, v35, v59
	v_add_f32_e32 v33, v33, v57
	v_max_f32_e32 v56, v147, v147
	v_add_f32_e32 v152, v34, v58
	v_max_f32_e32 v57, v148, v148
	v_mul_f32_e32 v59, 0xbfb8aa3b, v59
	v_mul_f32_e32 v33, 0xbfb8aa3b, v33
	v_max_f32_e32 v148, 0, v56
	v_add_f32_e32 v32, 1.0, v32
	s_nop 1
	v_cvt_pk_bf16_f32 v35, v149, v144
	v_mul_f32_e32 v144, 0xbfb8aa3b, v152
	v_exp_f32_e32 v59, v59
	v_exp_f32_e32 v33, v33
	v_sqrt_f32_e32 v148, v148
	v_rcp_f32_e32 v32, v32
	v_exp_f32_e32 v144, v144
	v_max_f32_e32 v147, v151, v151
	s_mov_b32 s0, 0x800000
	v_max_f32_e32 v150, v150, v150
	s_waitcnt lgkmcnt(0)
	v_and_b32_e32 v154, 0xffff0000, v104
	v_lshlrev_b32_e32 v104, 16, v104
	s_nop 1
	v_cvt_pk_bf16_f32 v34, v146, v145
	v_max_f32_e32 v146, 0, v57
	v_max_f32_e32 v147, 0, v147
	v_add_f32_e32 v59, 1.0, v59
	v_add_f32_e32 v33, 1.0, v33
	v_mul_f32_e32 v32, v32, v148
	v_max_f32_e32 v145, 0, v150
	v_sqrt_f32_e32 v146, v146
	v_sqrt_f32_e32 v147, v147
	v_add_f32_e32 v144, 1.0, v144
	v_rcp_f32_e32 v33, v33
	v_rcp_f32_e32 v59, v59
	v_mul_f32_e32 v32, v32, v104
	v_sqrt_f32_e32 v145, v145
	v_rcp_f32_e32 v144, v144
	v_lshlrev_b32_e32 v153, 16, v105
	v_and_b32_e32 v105, 0xffff0000, v105
	v_mul_f32_e32 v33, v33, v146
	v_mul_f32_e32 v59, v59, v147
	v_mul_f32_e32 v144, v144, v145
	v_mul_f32_e32 v33, v33, v154
	v_mul_f32_e32 v59, v59, v105
	v_mul_f32_e32 v144, v144, v153
	s_nop 1
	v_cvt_pk_bf16_f32 v32, v32, v33
	s_nop 1
	v_cvt_pk_bf16_f32 v33, v144, v59
	v_add_u32_e32 v58, v114, v110
	ds_read_b64 v[56:57], v58
	s_waitcnt vmcnt(1)
	v_mul_f32_e32 v40, 0xbfb8aa3b, v40
	v_exp_f32_e32 v40, v40
	s_nop 0
	v_add_f32_e32 v40, 1.0, v40
	v_cmp_gt_f32_e64 s[0:1], s0, v40
	s_nop 1
	v_cndmask_b32_e64 v104, 0, 32, s[0:1]
	v_ldexp_f32 v40, v40, v104
	v_log_f32_e32 v40, v40
	v_cndmask_b32_e64 v59, 0, v217, s[0:1]
	s_mov_b32 s0, 0x3f317217
	v_mul_f32_e32 v104, 0x3f317217, v40
	v_fma_f32 v104, v40, s0, -v104
	v_fmac_f32_e32 v104, 0x3377d1cf, v40
	s_mov_b32 s0, 0x7f800000
	v_fmac_f32_e32 v104, 0x3f317217, v40
	v_cmp_lt_f32_e64 s[0:1], |v40|, s0
	s_nop 1
	v_cndmask_b32_e64 v40, v40, v104, s[0:1]
	v_sub_f32_e32 v40, v40, v59
	v_mul_f32_e32 v59, 0xc1000000, v40
	v_lshlrev_b32_e32 v40, 16, v143
	v_mul_f32_e32 v40, v59, v40
	v_add_f32_e32 v104, v40, v40
	s_mov_b32 s0, 0xbca3d70a
	v_cmp_nlt_f32_e64 s[0:1], s0, v104
	s_mov_b32 s2, 0x3e2aaaab
	v_mul_f32_e32 v240, 0x3fb8aa3b, v104
	v_exp_f32_e32 v240, v240
	v_fma_f32 v241, v104, s2, 0.5
	v_fma_f32 v241, v104, v241, 1.0
	v_sub_f32_e32 v240, 1.0, v240
	v_mul_f32_e64 v241, v241, -v104
	v_cndmask_b32_e64 v144, v241, v240, s[0:1]
	v_mul_f32_e32 v41, 0xbfb8aa3b, v41
	v_exp_f32_e32 v41, v41
	s_mov_b32 s0, 0x800000
	v_add_f32_e32 v41, 1.0, v41
	v_cmp_gt_f32_e64 s[0:1], s0, v41
	s_nop 1
	v_cndmask_b32_e64 v104, 0, 32, s[0:1]
	v_ldexp_f32 v41, v41, v104
	v_log_f32_e32 v41, v41
	v_cndmask_b32_e64 v104, 0, v217, s[0:1]
	s_mov_b32 s0, 0x3f317217
	v_mul_f32_e32 v105, 0x3f317217, v41
	v_fma_f32 v105, v41, s0, -v105
	v_fmac_f32_e32 v105, 0x3377d1cf, v41
	s_mov_b32 s0, 0x7f800000
	v_fmac_f32_e32 v105, 0x3f317217, v41
	v_cmp_lt_f32_e64 s[0:1], |v41|, s0
	s_nop 1
	v_cndmask_b32_e64 v41, v41, v105, s[0:1]
	v_sub_f32_e32 v41, v41, v104
	v_mul_f32_e32 v104, 0xc1000000, v41
	v_and_b32_e32 v41, 0xffff0000, v143
	v_mul_f32_e32 v41, v104, v41
	v_add_f32_e32 v105, v41, v41
	s_mov_b32 s0, 0xbca3d70a
	v_cmp_nlt_f32_e64 s[0:1], s0, v105
	s_mov_b32 s2, 0x3e2aaaab
	v_mul_f32_e32 v240, 0x3fb8aa3b, v105
	v_exp_f32_e32 v240, v240
	v_fma_f32 v241, v105, s2, 0.5
	v_fma_f32 v241, v105, v241, 1.0
	v_sub_f32_e32 v240, 1.0, v240
	v_mul_f32_e64 v241, v241, -v105
	v_cndmask_b32_e64 v145, v241, v240, s[0:1]
	v_mul_f32_e32 v42, 0xbfb8aa3b, v42
	v_exp_f32_e32 v42, v42
	s_mov_b32 s0, 0x800000
	v_add_f32_e32 v42, 1.0, v42
	v_cmp_gt_f32_e64 s[0:1], s0, v42
	s_nop 1
	v_cndmask_b32_e64 v105, 0, 32, s[0:1]
	v_ldexp_f32 v42, v42, v105
	v_log_f32_e32 v42, v42
	v_cndmask_b32_e64 v105, 0, v217, s[0:1]
	s_mov_b32 s0, 0x3f317217
	v_mul_f32_e32 v143, 0x3f317217, v42
	v_fma_f32 v143, v42, s0, -v143
	v_fmac_f32_e32 v143, 0x3377d1cf, v42
	s_mov_b32 s0, 0x7f800000
	v_fmac_f32_e32 v143, 0x3f317217, v42
	v_cmp_lt_f32_e64 s[0:1], |v42|, s0
	s_nop 1
	v_cndmask_b32_e64 v42, v42, v143, s[0:1]
	v_sub_f32_e32 v42, v42, v105
	v_mul_f32_e32 v105, 0xc1000000, v42
	v_lshlrev_b32_e32 v42, 16, v142
	v_mul_f32_e32 v42, v105, v42
	v_add_f32_e32 v143, v42, v42
	s_mov_b32 s0, 0xbca3d70a
	v_cmp_nlt_f32_e64 s[0:1], s0, v143
	s_mov_b32 s2, 0x3e2aaaab
	v_mul_f32_e32 v240, 0x3fb8aa3b, v143
	v_exp_f32_e32 v240, v240
	v_fma_f32 v241, v143, s2, 0.5
	v_fma_f32 v241, v143, v241, 1.0
	v_sub_f32_e32 v240, 1.0, v240
	v_mul_f32_e64 v241, v241, -v143
	v_cndmask_b32_e64 v146, v241, v240, s[0:1]
	v_mul_f32_e32 v43, 0xbfb8aa3b, v43
	v_exp_f32_e32 v43, v43
	s_mov_b32 s0, 0x800000
	v_add_f32_e32 v43, 1.0, v43
	v_cmp_gt_f32_e64 s[0:1], s0, v43
	s_nop 1
	v_cndmask_b32_e64 v143, 0, 32, s[0:1]
	v_ldexp_f32 v43, v43, v143
	v_log_f32_e32 v43, v43
	v_cndmask_b32_e64 v143, 0, v217, s[0:1]
	s_mov_b32 s0, 0x3f317217
	v_mul_f32_e32 v147, 0x3f317217, v43
	v_fma_f32 v147, v43, s0, -v147
	v_fmac_f32_e32 v147, 0x3377d1cf, v43
	s_mov_b32 s0, 0x7f800000
	v_fmac_f32_e32 v147, 0x3f317217, v43
	v_cmp_lt_f32_e64 s[0:1], |v43|, s0
	s_nop 1
	v_cndmask_b32_e64 v43, v43, v147, s[0:1]
	v_sub_f32_e32 v43, v43, v143
	v_mul_f32_e32 v143, 0xc1000000, v43
	v_and_b32_e32 v43, 0xffff0000, v142
	v_mul_f32_e32 v43, v143, v43
	v_add_f32_e32 v147, v43, v43
	s_mov_b32 s0, 0xbca3d70a
	v_cmp_nlt_f32_e64 s[0:1], s0, v147
	s_mov_b32 s2, 0x3e2aaaab
	v_mul_f32_e32 v240, 0x3fb8aa3b, v147
	v_exp_f32_e32 v240, v240
	v_fma_f32 v241, v147, s2, 0.5
	v_fma_f32 v241, v147, v241, 1.0
	v_sub_f32_e32 v240, 1.0, v240
	v_mul_f32_e64 v241, v241, -v147
	v_cndmask_b32_e64 v142, v241, v240, s[0:1]
	s_waitcnt vmcnt(0)
	v_add_f32_e32 v30, v30, v38
	v_mul_f32_e32 v30, 0xbfb8aa3b, v30
	v_add_f32_e32 v29, v29, v37
	v_exp_f32_e32 v30, v30
	v_mul_f32_e32 v29, 0xbfb8aa3b, v29
	v_exp_f32_e32 v29, v29
	v_max_f32_e32 v146, v146, v146
	v_max_f32_e32 v146, 0, v146
	v_add_f32_e32 v30, 1.0, v30
	v_add_f32_e32 v31, v31, v39
	v_max_f32_e32 v145, v145, v145
	v_sqrt_f32_e32 v146, v146
	v_rcp_f32_e32 v30, v30
	v_mul_f32_e32 v31, 0xbfb8aa3b, v31
	v_add_f32_e32 v29, 1.0, v29
	v_max_f32_e32 v145, 0, v145
	v_exp_f32_e32 v31, v31
	v_rcp_f32_e32 v29, v29
	v_sqrt_f32_e32 v145, v145
	v_add_f32_e32 v28, v28, v36
	v_mul_f32_e32 v28, 0xbfb8aa3b, v28
	v_exp_f32_e32 v28, v28
	s_waitcnt lgkmcnt(0)
	v_lshlrev_b32_e32 v147, 16, v57
	v_mul_f32_e32 v30, v30, v146
	v_mul_f32_e32 v146, v30, v147
	v_add_f32_e32 v30, 1.0, v31
	v_and_b32_e32 v31, 0xffff0000, v56
	v_mul_f32_e32 v29, v29, v145
	v_mul_f32_e32 v29, v29, v31
	v_lshlrev_b32_e32 v31, 16, v56
	v_max_f32_e32 v56, v144, v144
	v_add_f32_e32 v28, 1.0, v28
	v_max_f32_e32 v56, 0, v56
	v_max_f32_e32 v142, v142, v142
	v_rcp_f32_e32 v28, v28
	v_sqrt_f32_e32 v56, v56
	v_max_f32_e32 v142, 0, v142
	v_rcp_f32_e32 v30, v30
	v_sqrt_f32_e32 v142, v142
	v_mul_f32_e32 v28, v28, v56
	v_mul_f32_e32 v28, v28, v31
	v_and_b32_e32 v31, 0xffff0000, v57
	v_mul_f32_e32 v30, v30, v142
	v_mul_f32_e32 v56, v30, v31
	s_nop 1
	v_cvt_pk_bf16_f32 v30, v40, v41
	v_add_u32_e32 v40, v114, v112
	ds_read_b64 v[40:41], v40
	s_nop 1
	v_cvt_pk_bf16_f32 v31, v42, v43
	v_lshlrev_b32_e32 v42, 16, v141
	v_mul_f32_e32 v42, v59, v42
	s_nop 1
	v_cvt_pk_bf16_f32 v28, v28, v29
	s_nop 1
	v_cvt_pk_bf16_f32 v29, v146, v56
	v_add_f32_e32 v56, v42, v42
	s_mov_b32 s0, 0xbca3d70a
	v_cmp_nlt_f32_e64 s[0:1], s0, v56
	s_mov_b32 s2, 0x3e2aaaab
	v_mul_f32_e32 v240, 0x3fb8aa3b, v56
	v_exp_f32_e32 v240, v240
	v_fma_f32 v241, v56, s2, 0.5
	v_fma_f32 v241, v56, v241, 1.0
	v_sub_f32_e32 v240, 1.0, v240
	v_mul_f32_e64 v241, v241, -v56
	v_cndmask_b32_e64 v43, v241, v240, s[0:1]
	v_and_b32_e32 v56, 0xffff0000, v141
	v_mul_f32_e32 v56, v104, v56
	v_add_f32_e32 v141, v56, v56
	s_mov_b32 s0, 0xbca3d70a
	v_cmp_nlt_f32_e64 s[0:1], s0, v141
	s_mov_b32 s2, 0x3e2aaaab
	v_mul_f32_e32 v240, 0x3fb8aa3b, v141
	v_exp_f32_e32 v240, v240
	v_fma_f32 v241, v141, s2, 0.5
	v_fma_f32 v241, v141, v241, 1.0
	v_sub_f32_e32 v240, 1.0, v240
	v_mul_f32_e64 v241, v241, -v141
	v_cndmask_b32_e64 v57, v241, v240, s[0:1]
	v_lshlrev_b32_e32 v141, 16, v140
	v_mul_f32_e32 v141, v105, v141
	v_add_f32_e32 v142, v141, v141
	s_mov_b32 s0, 0xbca3d70a
	v_cmp_nlt_f32_e64 s[0:1], s0, v142
	s_mov_b32 s2, 0x3e2aaaab
	v_mul_f32_e32 v240, 0x3fb8aa3b, v142
	v_exp_f32_e32 v240, v240
	v_fma_f32 v241, v142, s2, 0.5
	v_fma_f32 v241, v142, v241, 1.0
	v_sub_f32_e32 v240, 1.0, v240
	v_mul_f32_e64 v241, v241, -v142
	v_cndmask_b32_e64 v144, v241, v240, s[0:1]
	v_and_b32_e32 v140, 0xffff0000, v140
	v_mul_f32_e32 v140, v143, v140
	v_add_f32_e32 v145, v140, v140
	s_mov_b32 s0, 0xbca3d70a
	v_cmp_nlt_f32_e64 s[0:1], s0, v145
	s_mov_b32 s2, 0x3e2aaaab
	v_mul_f32_e32 v240, 0x3fb8aa3b, v145
	v_exp_f32_e32 v240, v240
	v_fma_f32 v241, v145, s2, 0.5
	v_fma_f32 v241, v145, v241, 1.0
	v_sub_f32_e32 v240, 1.0, v240
	v_mul_f32_e64 v241, v241, -v145
	v_cndmask_b32_e64 v142, v241, v240, s[0:1]
	v_add_f32_e32 v24, v24, v36
	v_mul_f32_e32 v24, 0xbfb8aa3b, v24
	v_exp_f32_e32 v24, v24
	v_max_f32_e32 v43, v43, v43
	v_add_f32_e32 v26, v26, v38
	v_add_f32_e32 v27, v27, v39
	v_add_f32_e32 v25, v25, v37
	v_add_f32_e32 v24, 1.0, v24
	v_max_f32_e32 v43, 0, v43
	v_mul_f32_e32 v26, 0xbfb8aa3b, v26
	v_mul_f32_e32 v27, 0xbfb8aa3b, v27
	v_mul_f32_e32 v25, 0xbfb8aa3b, v25
	v_rcp_f32_e32 v24, v24
	v_sqrt_f32_e32 v43, v43
	v_exp_f32_e32 v26, v26
	v_exp_f32_e32 v27, v27
	v_exp_f32_e32 v25, v25
	v_max_f32_e32 v144, v144, v144
	v_max_f32_e32 v57, v57, v57
	v_mul_f32_e32 v24, v24, v43
	v_max_f32_e32 v43, v142, v142
	v_max_f32_e32 v144, 0, v144
	v_add_f32_e32 v26, 1.0, v26
	v_add_f32_e32 v27, 1.0, v27
	v_add_f32_e32 v25, 1.0, v25
	v_max_f32_e32 v57, 0, v57
	v_max_f32_e32 v43, 0, v43
	v_sqrt_f32_e32 v144, v144
	v_rcp_f32_e32 v26, v26
	v_rcp_f32_e32 v25, v25
	v_sqrt_f32_e32 v57, v57
	v_rcp_f32_e32 v27, v27
	v_sqrt_f32_e32 v43, v43
	s_waitcnt lgkmcnt(0)
	v_lshlrev_b32_e32 v145, 16, v41
	v_mul_f32_e32 v26, v26, v144
	v_and_b32_e32 v144, 0xffff0000, v40
	v_mul_f32_e32 v25, v25, v57
	v_lshlrev_b32_e32 v40, 16, v40
	v_and_b32_e32 v41, 0xffff0000, v41
	v_mul_f32_e32 v27, v27, v43
	v_mul_f32_e32 v26, v26, v145
	v_mul_f32_e32 v25, v25, v144
	v_mul_f32_e32 v24, v24, v40
	v_mul_f32_e32 v27, v27, v41
	s_nop 1
	v_cvt_pk_bf16_f32 v24, v24, v25
	s_nop 1
	v_cvt_pk_bf16_f32 v25, v26, v27
	ds_read_b64 v[26:27], v58 offset:4096
	v_cndmask_b32_e32 v40, v42, v218, vcc
	v_lshlrev_b32_e32 v42, 16, v139
	v_cndmask_b32_e32 v56, v56, v218, vcc
	v_mul_f32_e32 v42, v59, v42
	s_nop 1
	v_cvt_pk_bf16_f32 v40, v40, v56
	v_add_f32_e32 v56, v42, v42
	s_mov_b32 s0, 0xbca3d70a
	v_cndmask_b32_e32 v41, v140, v218, vcc
	v_cmp_nlt_f32_e64 s[0:1], s0, v56
	v_cndmask_b32_e32 v141, v141, v218, vcc
	s_nop 1
	v_cvt_pk_bf16_f32 v41, v141, v41
	s_mov_b32 s2, 0x3e2aaaab
	v_mul_f32_e32 v240, 0x3fb8aa3b, v56
	v_exp_f32_e32 v240, v240
	v_fma_f32 v241, v56, s2, 0.5
	v_fma_f32 v241, v56, v241, 1.0
	v_sub_f32_e32 v240, 1.0, v240
	v_mul_f32_e64 v241, v241, -v56
	v_cndmask_b32_e64 v43, v241, v240, s[0:1]
	v_and_b32_e32 v56, 0xffff0000, v139
	v_mul_f32_e32 v56, v104, v56
	v_add_f32_e32 v57, v56, v56
	s_mov_b32 s0, 0xbca3d70a
	v_cmp_nlt_f32_e64 s[0:1], s0, v57
	s_mov_b32 s2, 0x3e2aaaab
	v_mul_f32_e32 v240, 0x3fb8aa3b, v57
	v_exp_f32_e32 v240, v240
	v_fma_f32 v241, v57, s2, 0.5
	v_fma_f32 v241, v57, v241, 1.0
	v_sub_f32_e32 v240, 1.0, v240
	v_mul_f32_e64 v241, v241, -v57
	v_cndmask_b32_e64 v139, v241, v240, s[0:1]
	v_lshlrev_b32_e32 v57, 16, v138
	v_mul_f32_e32 v57, v105, v57
	v_add_f32_e32 v140, v57, v57
	s_mov_b32 s0, 0xbca3d70a
	v_cmp_nlt_f32_e64 s[0:1], s0, v140
	s_mov_b32 s2, 0x3e2aaaab
	v_mul_f32_e32 v240, 0x3fb8aa3b, v140
	v_exp_f32_e32 v240, v240
	v_fma_f32 v241, v140, s2, 0.5
	v_fma_f32 v241, v140, v241, 1.0
	v_sub_f32_e32 v240, 1.0, v240
	v_mul_f32_e64 v241, v241, -v140
	v_cndmask_b32_e64 v141, v241, v240, s[0:1]
	v_and_b32_e32 v138, 0xffff0000, v138
	v_mul_f32_e32 v138, v143, v138
	v_add_f32_e32 v142, v138, v138
	s_mov_b32 s0, 0xbca3d70a
	v_cmp_nlt_f32_e64 s[0:1], s0, v142
	s_mov_b32 s2, 0x3e2aaaab
	v_mul_f32_e32 v240, 0x3fb8aa3b, v142
	v_exp_f32_e32 v240, v240
	v_fma_f32 v241, v142, s2, 0.5
	v_fma_f32 v241, v142, v241, 1.0
	v_sub_f32_e32 v240, 1.0, v240
	v_mul_f32_e64 v241, v241, -v142
	v_cndmask_b32_e64 v140, v241, v240, s[0:1]
	v_add_f32_e32 v21, v21, v37
	v_mul_f32_e32 v21, 0xbfb8aa3b, v21
	v_exp_f32_e32 v21, v21
	v_add_f32_e32 v22, v22, v38
	v_max_f32_e32 v139, v139, v139
	v_add_f32_e32 v20, v20, v36
	v_mul_f32_e32 v22, 0xbfb8aa3b, v22
	v_add_f32_e32 v23, v23, v39
	v_add_f32_e32 v21, 1.0, v21
	v_max_f32_e32 v139, 0, v139
	v_mul_f32_e32 v20, 0xbfb8aa3b, v20
	v_exp_f32_e32 v22, v22
	v_mul_f32_e32 v23, 0xbfb8aa3b, v23
	v_rcp_f32_e32 v21, v21
	v_sqrt_f32_e32 v139, v139
	v_exp_f32_e32 v20, v20
	v_exp_f32_e32 v23, v23
	v_max_f32_e32 v141, v141, v141
	v_max_f32_e32 v43, v43, v43
	v_max_f32_e32 v141, 0, v141
	v_add_f32_e32 v22, 1.0, v22
	v_mul_f32_e32 v21, v21, v139
	v_add_f32_e32 v20, 1.0, v20
	v_max_f32_e32 v43, 0, v43
	v_max_f32_e32 v139, v140, v140
	v_sqrt_f32_e32 v141, v141
	v_rcp_f32_e32 v22, v22
	v_add_f32_e32 v23, 1.0, v23
	v_rcp_f32_e32 v20, v20
	v_sqrt_f32_e32 v43, v43
	v_max_f32_e32 v139, 0, v139
	v_rcp_f32_e32 v23, v23
	v_sqrt_f32_e32 v139, v139
	v_mul_f32_e32 v22, v22, v141
	s_waitcnt lgkmcnt(0)
	v_and_b32_e32 v141, 0xffff0000, v26
	v_lshlrev_b32_e32 v26, 16, v26
	v_mul_f32_e32 v20, v20, v43
	v_lshlrev_b32_e32 v142, 16, v27
	v_mul_f32_e32 v21, v21, v141
	v_mul_f32_e32 v20, v20, v26
	v_and_b32_e32 v26, 0xffff0000, v27
	v_mul_f32_e32 v23, v23, v139
	v_mul_f32_e32 v22, v22, v142
	v_mul_f32_e32 v23, v23, v26
	s_nop 1
	v_cvt_pk_bf16_f32 v26, v20, v21
	ds_read_b64 v[20:21], v58 offset:6144
	s_nop 1
	v_cvt_pk_bf16_f32 v27, v22, v23
	v_lshlrev_b32_e32 v22, 16, v137
	v_mul_f32_e32 v22, v59, v22
	s_nop 1
	v_cvt_pk_bf16_f32 v42, v42, v56
	v_add_f32_e32 v56, v22, v22
	s_mov_b32 s0, 0xbca3d70a
	v_cmp_nlt_f32_e64 s[0:1], s0, v56
	s_nop 1
	v_cvt_pk_bf16_f32 v43, v57, v138
	s_mov_b32 s2, 0x3e2aaaab
	v_mul_f32_e32 v240, 0x3fb8aa3b, v56
	v_exp_f32_e32 v240, v240
	v_fma_f32 v241, v56, s2, 0.5
	v_fma_f32 v241, v56, v241, 1.0
	v_sub_f32_e32 v240, 1.0, v240
	v_mul_f32_e64 v241, v241, -v56
	v_cndmask_b32_e64 v23, v241, v240, s[0:1]
	v_and_b32_e32 v56, 0xffff0000, v137
	v_mul_f32_e32 v56, v104, v56
	v_add_f32_e32 v58, v56, v56
	s_mov_b32 s0, 0xbca3d70a
	v_cmp_nlt_f32_e64 s[0:1], s0, v58
	s_mov_b32 s2, 0x3e2aaaab
	v_mul_f32_e32 v240, 0x3fb8aa3b, v58
	v_exp_f32_e32 v240, v240
	v_fma_f32 v241, v58, s2, 0.5
	v_fma_f32 v241, v58, v241, 1.0
	v_sub_f32_e32 v240, 1.0, v240
	v_mul_f32_e64 v241, v241, -v58
	v_cndmask_b32_e64 v57, v241, v240, s[0:1]
	v_lshlrev_b32_e32 v58, 16, v136
	v_mul_f32_e32 v58, v105, v58
	v_add_f32_e32 v59, v58, v58
	s_mov_b32 s0, 0xbca3d70a
	v_cmp_nlt_f32_e64 s[0:1], s0, v59
	s_mov_b32 s2, 0x3e2aaaab
	v_mul_f32_e32 v240, 0x3fb8aa3b, v59
	v_exp_f32_e32 v240, v240
	v_fma_f32 v241, v59, s2, 0.5
	v_fma_f32 v241, v59, v241, 1.0
	v_sub_f32_e32 v240, 1.0, v240
	v_mul_f32_e64 v241, v241, -v59
	v_cndmask_b32_e64 v104, v241, v240, s[0:1]
	v_and_b32_e32 v59, 0xffff0000, v136
	v_mul_f32_e32 v59, v143, v59
	v_add_f32_e32 v136, v59, v59
	s_mov_b32 s0, 0xbca3d70a
	v_cmp_nlt_f32_e64 s[0:1], s0, v136
	s_mov_b32 s2, 0x3e2aaaab
	v_mul_f32_e32 v240, 0x3fb8aa3b, v136
	v_exp_f32_e32 v240, v240
	v_fma_f32 v241, v136, s2, 0.5
	v_fma_f32 v241, v136, v241, 1.0
	v_sub_f32_e32 v240, 1.0, v240
	v_mul_f32_e64 v241, v241, -v136
	v_cndmask_b32_e64 v105, v241, v240, s[0:1]
	v_add_f32_e32 v18, v18, v38
	v_add_f32_e32 v16, v16, v36
	v_mul_f32_e32 v18, 0xbfb8aa3b, v18
	v_mul_f32_e32 v16, 0xbfb8aa3b, v16
	v_exp_f32_e32 v18, v18
	v_exp_f32_e32 v16, v16
	v_max_f32_e32 v104, v104, v104
	v_max_f32_e32 v23, v23, v23
	v_add_f32_e32 v18, 1.0, v18
	v_max_f32_e32 v104, 0, v104
	v_add_f32_e32 v16, 1.0, v16
	v_max_f32_e32 v23, 0, v23
	v_rcp_f32_e32 v18, v18
	v_sqrt_f32_e32 v104, v104
	v_add_f32_e32 v19, v19, v39
	v_add_f32_e32 v17, v17, v37
	v_rcp_f32_e32 v16, v16
	v_sqrt_f32_e32 v23, v23
	v_mul_f32_e32 v19, 0xbfb8aa3b, v19
	v_mul_f32_e32 v17, 0xbfb8aa3b, v17
	v_exp_f32_e32 v19, v19
	v_exp_f32_e32 v17, v17
	s_waitcnt lgkmcnt(0)
	v_lshlrev_b32_e32 v38, 16, v21
	v_mul_f32_e32 v18, v18, v104
	v_and_b32_e32 v37, 0xffff0000, v20
	v_lshlrev_b32_e32 v20, 16, v20
	v_mul_f32_e32 v16, v16, v23
	v_mul_f32_e32 v18, v18, v38
	v_max_f32_e32 v38, v57, v57
	v_mul_f32_e32 v16, v16, v20
	v_and_b32_e32 v20, 0xffff0000, v21
	v_max_f32_e32 v21, v105, v105
	v_add_f32_e32 v19, 1.0, v19
	v_add_f32_e32 v17, 1.0, v17
	v_max_f32_e32 v38, 0, v38
	v_max_f32_e32 v21, 0, v21
	v_rcp_f32_e32 v19, v19
	v_rcp_f32_e32 v17, v17
	v_sqrt_f32_e32 v38, v38
	v_sqrt_f32_e32 v21, v21
	s_mov_b32 s0, 0x800000
	s_mov_b32 s2, 0x3f317217
	v_mul_f32_e32 v17, v17, v38
	v_mul_f32_e32 v19, v19, v21
	v_mul_f32_e32 v17, v17, v37
	v_mul_f32_e32 v19, v19, v20
	s_nop 1
	v_cvt_pk_bf16_f32 v38, v22, v56
	s_nop 1
	v_cvt_pk_bf16_f32 v36, v16, v17
	s_nop 1
	v_cvt_pk_bf16_f32 v37, v18, v19
	global_load_dwordx4 v[16:19], v[102:103], off offset:192
	global_load_dwordx4 v[20:23], v[100:101], off offset:192
	s_nop 1
	v_cvt_pk_bf16_f32 v39, v58, v59
	v_add_u32_e32 v59, v115, v110
	s_waitcnt vmcnt(0)
	v_mul_f32_e32 v20, 0xbfb8aa3b, v20
	v_exp_f32_e32 v20, v20
	s_nop 0
	v_add_f32_e32 v20, 1.0, v20
	v_cmp_gt_f32_e64 s[0:1], s0, v20
	s_nop 1
	v_cndmask_b32_e64 v56, 0, 32, s[0:1]
	v_ldexp_f32 v20, v20, v56
	v_log_f32_e32 v20, v20
	s_nop 0
	v_mul_f32_e32 v56, 0x3f317217, v20
	v_fma_f32 v56, v20, s2, -v56
	v_fmac_f32_e32 v56, 0x3377d1cf, v20
	s_mov_b32 s2, 0x7f800000
	v_fmac_f32_e32 v56, 0x3f317217, v20
	v_cmp_lt_f32_e64 s[4:5], |v20|, s2
	s_nop 1
	v_cndmask_b32_e64 v20, v20, v56, s[4:5]
	v_cndmask_b32_e64 v56, 0, v217, s[0:1]
	v_sub_f32_e32 v20, v20, v56
	ds_read_b64 v[56:57], v59
	v_mul_f32_e32 v58, 0xc1000000, v20
	v_lshlrev_b32_e32 v20, 16, v135
	v_mul_f32_e32 v20, v58, v20
	v_add_f32_e32 v100, v20, v20
	s_mov_b32 s0, 0xbca3d70a
	v_cmp_nlt_f32_e64 s[0:1], s0, v100
	s_mov_b32 s2, 0x3e2aaaab
	v_mul_f32_e32 v240, 0x3fb8aa3b, v100
	v_exp_f32_e32 v240, v240
	v_fma_f32 v241, v100, s2, 0.5
	v_fma_f32 v241, v100, v241, 1.0
	v_sub_f32_e32 v240, 1.0, v240
	v_mul_f32_e64 v241, v241, -v100
	v_cndmask_b32_e64 v101, v241, v240, s[0:1]
	v_mul_f32_e32 v21, 0xbfb8aa3b, v21
	v_exp_f32_e32 v21, v21
	s_mov_b32 s0, 0x800000
	v_add_f32_e32 v21, 1.0, v21
	v_cmp_gt_f32_e64 s[0:1], s0, v21
	s_nop 1
	v_cndmask_b32_e64 v100, 0, 32, s[0:1]
	v_ldexp_f32 v21, v21, v100
	v_log_f32_e32 v21, v21
	v_cndmask_b32_e64 v100, 0, v217, s[0:1]
	s_mov_b32 s0, 0x3f317217
	v_mul_f32_e32 v102, 0x3f317217, v21
	v_fma_f32 v102, v21, s0, -v102
	v_fmac_f32_e32 v102, 0x3377d1cf, v21
	s_mov_b32 s0, 0x7f800000
	v_fmac_f32_e32 v102, 0x3f317217, v21
	v_cmp_lt_f32_e64 s[0:1], |v21|, s0
	s_nop 1
	v_cndmask_b32_e64 v21, v21, v102, s[0:1]
	v_sub_f32_e32 v21, v21, v100
	v_mul_f32_e32 v100, 0xc1000000, v21
	v_and_b32_e32 v21, 0xffff0000, v135
	v_mul_f32_e32 v21, v100, v21
	v_add_f32_e32 v103, v21, v21
	s_mov_b32 s0, 0xbca3d70a
	v_cmp_nlt_f32_e64 s[0:1], s0, v103
	s_mov_b32 s2, 0x3e2aaaab
	v_mul_f32_e32 v240, 0x3fb8aa3b, v103
	v_exp_f32_e32 v240, v240
	v_fma_f32 v241, v103, s2, 0.5
	v_fma_f32 v241, v103, v241, 1.0
	v_sub_f32_e32 v240, 1.0, v240
	v_mul_f32_e64 v241, v241, -v103
	v_cndmask_b32_e64 v102, v241, v240, s[0:1]
	v_mul_f32_e32 v22, 0xbfb8aa3b, v22
	v_exp_f32_e32 v22, v22
	s_mov_b32 s0, 0x800000
	v_add_f32_e32 v22, 1.0, v22
	v_cmp_gt_f32_e64 s[0:1], s0, v22
	s_nop 1
	v_cndmask_b32_e64 v103, 0, 32, s[0:1]
	v_ldexp_f32 v22, v22, v103
	v_log_f32_e32 v22, v22
	v_cndmask_b32_e64 v103, 0, v217, s[0:1]
	s_mov_b32 s0, 0x3f317217
	v_mul_f32_e32 v104, 0x3f317217, v22
	v_fma_f32 v104, v22, s0, -v104
	v_fmac_f32_e32 v104, 0x3377d1cf, v22
	s_mov_b32 s0, 0x7f800000
	v_fmac_f32_e32 v104, 0x3f317217, v22
	v_cmp_lt_f32_e64 s[0:1], |v22|, s0
	s_nop 1
	v_cndmask_b32_e64 v22, v22, v104, s[0:1]
	v_sub_f32_e32 v22, v22, v103
	v_mul_f32_e32 v22, 0xc1000000, v22
	v_lshlrev_b32_e32 v103, 16, v134
	v_mul_f32_e32 v103, v22, v103
	v_add_f32_e32 v105, v103, v103
	s_mov_b32 s0, 0xbca3d70a
	v_cmp_nlt_f32_e64 s[0:1], s0, v105
	s_mov_b32 s2, 0x3e2aaaab
	v_mul_f32_e32 v240, 0x3fb8aa3b, v105
	v_exp_f32_e32 v240, v240
	v_fma_f32 v241, v105, s2, 0.5
	v_fma_f32 v241, v105, v241, 1.0
	v_sub_f32_e32 v240, 1.0, v240
	v_mul_f32_e64 v241, v241, -v105
	v_cndmask_b32_e64 v104, v241, v240, s[0:1]
	v_mul_f32_e32 v23, 0xbfb8aa3b, v23
	v_exp_f32_e32 v23, v23
	s_mov_b32 s0, 0x800000
	v_add_f32_e32 v23, 1.0, v23
	v_cmp_gt_f32_e64 s[0:1], s0, v23
	s_nop 1
	v_cndmask_b32_e64 v105, 0, 32, s[0:1]
	v_ldexp_f32 v23, v23, v105
	v_log_f32_e32 v23, v23
	v_cndmask_b32_e64 v105, 0, v217, s[0:1]
	s_mov_b32 s0, 0x3f317217
	v_mul_f32_e32 v135, 0x3f317217, v23
	v_fma_f32 v135, v23, s0, -v135
	v_fmac_f32_e32 v135, 0x3377d1cf, v23
	s_mov_b32 s0, 0x7f800000
	v_fmac_f32_e32 v135, 0x3f317217, v23
	v_cmp_lt_f32_e64 s[0:1], |v23|, s0
	s_nop 1
	v_cndmask_b32_e64 v23, v23, v135, s[0:1]
	v_sub_f32_e32 v23, v23, v105
	v_mul_f32_e32 v23, 0xc1000000, v23
	v_and_b32_e32 v105, 0xffff0000, v134
	v_mul_f32_e32 v105, v23, v105
	v_add_f32_e32 v135, v105, v105
	s_mov_b32 s0, 0xbca3d70a
	v_cmp_nlt_f32_e64 s[0:1], s0, v135
	s_mov_b32 s2, 0x3e2aaaab
	v_mul_f32_e32 v240, 0x3fb8aa3b, v135
	v_exp_f32_e32 v240, v240
	v_fma_f32 v241, v135, s2, 0.5
	v_fma_f32 v241, v135, v241, 1.0
	v_sub_f32_e32 v240, 1.0, v240
	v_mul_f32_e64 v241, v241, -v135
	v_cndmask_b32_e64 v134, v241, v240, s[0:1]
	v_add_f32_e32 v14, v14, v18
	v_mul_f32_e32 v14, 0xbfb8aa3b, v14
	v_add_f32_e32 v13, v13, v17
	v_exp_f32_e32 v14, v14
	v_mul_f32_e32 v13, 0xbfb8aa3b, v13
	v_exp_f32_e32 v13, v13
	v_max_f32_e32 v104, v104, v104
	v_max_f32_e32 v104, 0, v104
	v_add_f32_e32 v14, 1.0, v14
	v_add_f32_e32 v15, v15, v19
	v_max_f32_e32 v102, v102, v102
	v_sqrt_f32_e32 v104, v104
	v_rcp_f32_e32 v14, v14
	v_mul_f32_e32 v15, 0xbfb8aa3b, v15
	v_add_f32_e32 v13, 1.0, v13
	v_max_f32_e32 v102, 0, v102
	v_exp_f32_e32 v15, v15
	v_rcp_f32_e32 v13, v13
	v_sqrt_f32_e32 v102, v102
	v_add_f32_e32 v12, v12, v16
	v_mul_f32_e32 v12, 0xbfb8aa3b, v12
	v_exp_f32_e32 v12, v12
	s_waitcnt lgkmcnt(0)
	v_lshlrev_b32_e32 v135, 16, v57
	v_mul_f32_e32 v14, v14, v104
	v_mul_f32_e32 v104, v14, v135
	v_add_f32_e32 v14, 1.0, v15
	v_and_b32_e32 v15, 0xffff0000, v56
	v_mul_f32_e32 v13, v13, v102
	v_mul_f32_e32 v13, v13, v15
	v_lshlrev_b32_e32 v15, 16, v56
	v_max_f32_e32 v56, v101, v101
	v_add_f32_e32 v12, 1.0, v12
	v_max_f32_e32 v56, 0, v56
	v_max_f32_e32 v101, v134, v134
	v_rcp_f32_e32 v12, v12
	v_sqrt_f32_e32 v56, v56
	v_max_f32_e32 v101, 0, v101
	v_rcp_f32_e32 v14, v14
	v_sqrt_f32_e32 v101, v101
	v_mul_f32_e32 v12, v12, v56
	v_mul_f32_e32 v12, v12, v15
	v_and_b32_e32 v15, 0xffff0000, v57
	v_mul_f32_e32 v14, v14, v101
	v_mul_f32_e32 v56, v14, v15
	s_nop 1
	v_cvt_pk_bf16_f32 v14, v20, v21
	v_add_u32_e32 v20, v115, v112
	ds_read_b64 v[20:21], v20
	s_nop 1
	v_cvt_pk_bf16_f32 v12, v12, v13
	s_nop 1
	v_cvt_pk_bf16_f32 v13, v104, v56
	v_lshlrev_b32_e32 v56, 16, v133
	v_mul_f32_e32 v56, v58, v56
	v_add_f32_e32 v101, v56, v56
	s_mov_b32 s0, 0xbca3d70a
	v_cmp_nlt_f32_e64 s[0:1], s0, v101
	s_nop 1
	v_cvt_pk_bf16_f32 v15, v103, v105
	s_mov_b32 s2, 0x3e2aaaab
	v_mul_f32_e32 v240, 0x3fb8aa3b, v101
	v_exp_f32_e32 v240, v240
	v_fma_f32 v241, v101, s2, 0.5
	v_fma_f32 v241, v101, v241, 1.0
	v_sub_f32_e32 v240, 1.0, v240
	v_mul_f32_e64 v241, v241, -v101
	v_cndmask_b32_e64 v57, v241, v240, s[0:1]
	v_and_b32_e32 v101, 0xffff0000, v133
	v_mul_f32_e32 v101, v100, v101
	v_add_f32_e32 v103, v101, v101
	s_mov_b32 s0, 0xbca3d70a
	v_cmp_nlt_f32_e64 s[0:1], s0, v103
	s_mov_b32 s2, 0x3e2aaaab
	v_mul_f32_e32 v240, 0x3fb8aa3b, v103
	v_exp_f32_e32 v240, v240
	v_fma_f32 v241, v103, s2, 0.5
	v_fma_f32 v241, v103, v241, 1.0
	v_sub_f32_e32 v240, 1.0, v240
	v_mul_f32_e64 v241, v241, -v103
	v_cndmask_b32_e64 v102, v241, v240, s[0:1]
	v_lshlrev_b32_e32 v103, 16, v132
	v_mul_f32_e32 v104, v22, v103
	v_add_f32_e32 v103, v104, v104
	s_mov_b32 s0, 0xbca3d70a
	v_cmp_nlt_f32_e64 s[0:1], s0, v103
	s_mov_b32 s2, 0x3e2aaaab
	v_mul_f32_e32 v240, 0x3fb8aa3b, v103
	v_exp_f32_e32 v240, v240
	v_fma_f32 v241, v103, s2, 0.5
	v_fma_f32 v241, v103, v241, 1.0
	v_sub_f32_e32 v240, 1.0, v240
	v_mul_f32_e64 v241, v241, -v103
	v_cndmask_b32_e64 v133, v241, v240, s[0:1]
	v_and_b32_e32 v103, 0xffff0000, v132
	v_mul_f32_e32 v103, v23, v103
	v_add_f32_e32 v132, v103, v103
	s_mov_b32 s0, 0xbca3d70a
	v_cmp_nlt_f32_e64 s[0:1], s0, v132
	s_mov_b32 s2, 0x3e2aaaab
	v_mul_f32_e32 v240, 0x3fb8aa3b, v132
	v_exp_f32_e32 v240, v240
	v_fma_f32 v241, v132, s2, 0.5
	v_fma_f32 v241, v132, v241, 1.0
	v_sub_f32_e32 v240, 1.0, v240
	v_mul_f32_e64 v241, v241, -v132
	v_cndmask_b32_e64 v105, v241, v240, s[0:1]
	v_add_f32_e32 v10, v10, v18
	v_mul_f32_e32 v10, 0xbfb8aa3b, v10
	v_exp_f32_e32 v10, v10
	v_max_f32_e32 v132, v133, v133
	v_max_f32_e32 v132, 0, v132
	v_add_f32_e32 v11, v11, v19
	v_add_f32_e32 v10, 1.0, v10
	v_sqrt_f32_e32 v132, v132
	v_rcp_f32_e32 v10, v10
	v_mul_f32_e32 v11, 0xbfb8aa3b, v11
	v_add_f32_e32 v9, v9, v17
	v_exp_f32_e32 v11, v11
	v_mul_f32_e32 v9, 0xbfb8aa3b, v9
	v_exp_f32_e32 v9, v9
	s_waitcnt lgkmcnt(0)
	v_lshlrev_b32_e32 v133, 16, v21
	v_mul_f32_e32 v10, v10, v132
	v_mul_f32_e32 v132, v10, v133
	v_add_f32_e32 v10, 1.0, v11
	v_max_f32_e32 v11, v102, v102
	v_add_f32_e32 v9, 1.0, v9
	v_max_f32_e32 v11, 0, v11
	v_add_f32_e32 v8, v8, v16
	v_rcp_f32_e32 v9, v9
	v_sqrt_f32_e32 v11, v11
	v_mul_f32_e32 v8, 0xbfb8aa3b, v8
	v_exp_f32_e32 v8, v8
	v_rcp_f32_e32 v10, v10
	v_mul_f32_e32 v9, v9, v11
	v_max_f32_e32 v11, v57, v57
	v_add_f32_e32 v8, 1.0, v8
	v_max_f32_e32 v11, 0, v11
	v_rcp_f32_e32 v8, v8
	v_sqrt_f32_e32 v11, v11
	v_and_b32_e32 v102, 0xffff0000, v20
	v_lshlrev_b32_e32 v20, 16, v20
	v_and_b32_e32 v21, 0xffff0000, v21
	v_mul_f32_e32 v8, v8, v11
	v_max_f32_e32 v11, v105, v105
	v_max_f32_e32 v11, 0, v11
	v_sqrt_f32_e32 v11, v11
	v_mul_f32_e32 v9, v9, v102
	v_mul_f32_e32 v8, v8, v20
	v_cndmask_b32_e32 v20, v56, v218, vcc
	v_mul_f32_e32 v10, v10, v11
	v_mul_f32_e32 v21, v10, v21
	v_cndmask_b32_e32 v57, v101, v218, vcc
	s_nop 1
	v_cvt_pk_bf16_f32 v10, v20, v57
	s_nop 1
	v_cvt_pk_bf16_f32 v8, v8, v9
	s_nop 1
	v_cvt_pk_bf16_f32 v9, v132, v21
	ds_read_b64 v[20:21], v59 offset:4096
	v_lshlrev_b32_e32 v56, 16, v131
	v_mul_f32_e32 v56, v58, v56
	v_add_f32_e32 v101, v56, v56
	s_mov_b32 s0, 0xbca3d70a
	v_cndmask_b32_e32 v104, v104, v218, vcc
	v_cndmask_b32_e32 v11, v103, v218, vcc
	v_cmp_nlt_f32_e32 vcc, s0, v101
	s_nop 1
	v_cvt_pk_bf16_f32 v11, v104, v11
	s_mov_b32 s2, 0x3e2aaaab
	v_mul_f32_e32 v240, 0x3fb8aa3b, v101
	v_exp_f32_e32 v240, v240
	v_fma_f32 v241, v101, s2, 0.5
	v_fma_f32 v241, v101, v241, 1.0
	v_sub_f32_e32 v240, 1.0, v240
	v_mul_f32_e64 v241, v241, -v101
	v_cndmask_b32_e32 v57, v241, v240, vcc
	v_and_b32_e32 v101, 0xffff0000, v131
	v_mul_f32_e32 v101, v100, v101
	v_add_f32_e32 v102, v101, v101
	s_mov_b32 s0, 0xbca3d70a
	v_cmp_nlt_f32_e32 vcc, s0, v102
	s_mov_b32 s2, 0x3e2aaaab
	v_mul_f32_e32 v240, 0x3fb8aa3b, v102
	v_exp_f32_e32 v240, v240
	v_fma_f32 v241, v102, s2, 0.5
	v_fma_f32 v241, v102, v241, 1.0
	v_sub_f32_e32 v240, 1.0, v240
	v_mul_f32_e64 v241, v241, -v102
	v_cndmask_b32_e32 v103, v241, v240, vcc
	v_lshlrev_b32_e32 v102, 16, v130
	v_mul_f32_e32 v102, v22, v102
	v_add_f32_e32 v104, v102, v102
	s_mov_b32 s0, 0xbca3d70a
	v_cmp_nlt_f32_e32 vcc, s0, v104
	s_mov_b32 s2, 0x3e2aaaab
	v_mul_f32_e32 v240, 0x3fb8aa3b, v104
	v_exp_f32_e32 v240, v240
	v_fma_f32 v241, v104, s2, 0.5
	v_fma_f32 v241, v104, v241, 1.0
	v_sub_f32_e32 v240, 1.0, v240
	v_mul_f32_e64 v241, v241, -v104
	v_cndmask_b32_e32 v131, v241, v240, vcc
	v_and_b32_e32 v104, 0xffff0000, v130
	v_mul_f32_e32 v104, v23, v104
	v_add_f32_e32 v130, v104, v104
	s_mov_b32 s0, 0xbca3d70a
	v_cmp_nlt_f32_e32 vcc, s0, v130
	s_mov_b32 s2, 0x3e2aaaab
	v_mul_f32_e32 v240, 0x3fb8aa3b, v130
	v_exp_f32_e32 v240, v240
	v_fma_f32 v241, v130, s2, 0.5
	v_fma_f32 v241, v130, v241, 1.0
	v_sub_f32_e32 v240, 1.0, v240
	v_mul_f32_e64 v241, v241, -v130
	v_cndmask_b32_e32 v105, v241, v240, vcc
	v_add_f32_e32 v6, v6, v18
	v_mul_f32_e32 v6, 0xbfb8aa3b, v6
	v_add_f32_e32 v5, v5, v17
	v_exp_f32_e32 v6, v6
	v_mul_f32_e32 v5, 0xbfb8aa3b, v5
	v_exp_f32_e32 v5, v5
	v_max_f32_e32 v130, v131, v131
	v_max_f32_e32 v130, 0, v130
	v_add_f32_e32 v6, 1.0, v6
	v_add_f32_e32 v7, v7, v19
	v_max_f32_e32 v103, v103, v103
	v_sqrt_f32_e32 v130, v130
	v_rcp_f32_e32 v6, v6
	v_mul_f32_e32 v7, 0xbfb8aa3b, v7
	v_add_f32_e32 v5, 1.0, v5
	v_max_f32_e32 v103, 0, v103
	v_exp_f32_e32 v7, v7
	v_rcp_f32_e32 v5, v5
	v_sqrt_f32_e32 v103, v103
	v_add_f32_e32 v4, v4, v16
	v_mul_f32_e32 v4, 0xbfb8aa3b, v4
	v_exp_f32_e32 v4, v4
	s_waitcnt lgkmcnt(0)
	v_lshlrev_b32_e32 v131, 16, v21
	v_mul_f32_e32 v6, v6, v130
	v_mul_f32_e32 v130, v6, v131
	v_add_f32_e32 v6, 1.0, v7
	v_and_b32_e32 v7, 0xffff0000, v20
	v_mul_f32_e32 v5, v5, v103
	v_mul_f32_e32 v5, v5, v7
	v_lshlrev_b32_e32 v7, 16, v20
	v_max_f32_e32 v20, v57, v57
	v_add_f32_e32 v4, 1.0, v4
	v_max_f32_e32 v20, 0, v20
	v_max_f32_e32 v57, v105, v105
	v_rcp_f32_e32 v4, v4
	v_sqrt_f32_e32 v20, v20
	v_max_f32_e32 v57, 0, v57
	v_rcp_f32_e32 v6, v6
	v_sqrt_f32_e32 v57, v57
	v_mul_f32_e32 v4, v4, v20
	v_mul_f32_e32 v4, v4, v7
	v_and_b32_e32 v7, 0xffff0000, v21
	v_mul_f32_e32 v6, v6, v57
	v_mul_f32_e32 v20, v6, v7
	s_nop 1
	v_cvt_pk_bf16_f32 v4, v4, v5
	s_nop 1
	v_cvt_pk_bf16_f32 v5, v130, v20
	ds_read_b64 v[20:21], v59 offset:6144
	s_nop 1
	v_cvt_pk_bf16_f32 v6, v56, v101
	v_lshlrev_b32_e32 v56, 16, v129
	v_mul_f32_e32 v56, v58, v56
	v_add_f32_e32 v57, v56, v56
	s_mov_b32 s0, 0xbca3d70a
	v_cmp_nlt_f32_e32 vcc, s0, v57
	s_nop 1
	v_cvt_pk_bf16_f32 v7, v102, v104
	s_mov_b32 s2, 0x3e2aaaab
	v_mul_f32_e32 v240, 0x3fb8aa3b, v57
	v_exp_f32_e32 v240, v240
	v_fma_f32 v241, v57, s2, 0.5
	v_fma_f32 v241, v57, v241, 1.0
	v_sub_f32_e32 v240, 1.0, v240
	v_mul_f32_e64 v241, v241, -v57
	v_cndmask_b32_e32 v58, v241, v240, vcc
	v_and_b32_e32 v57, 0xffff0000, v129
	v_mul_f32_e32 v57, v100, v57
	v_add_f32_e32 v59, v57, v57
	s_mov_b32 s0, 0xbca3d70a
	v_cmp_nlt_f32_e32 vcc, s0, v59
	s_mov_b32 s2, 0x3e2aaaab
	v_mul_f32_e32 v240, 0x3fb8aa3b, v59
	v_exp_f32_e32 v240, v240
	v_fma_f32 v241, v59, s2, 0.5
	v_fma_f32 v241, v59, v241, 1.0
	v_sub_f32_e32 v240, 1.0, v240
	v_mul_f32_e64 v241, v241, -v59
	v_cndmask_b32_e32 v100, v241, v240, vcc
	v_lshlrev_b32_e32 v59, 16, v128
	v_mul_f32_e32 v22, v22, v59
	v_add_f32_e32 v59, v22, v22
	s_mov_b32 s0, 0xbca3d70a
	v_cmp_nlt_f32_e32 vcc, s0, v59
	s_mov_b32 s2, 0x3e2aaaab
	v_mul_f32_e32 v240, 0x3fb8aa3b, v59
	v_exp_f32_e32 v240, v240
	v_fma_f32 v241, v59, s2, 0.5
	v_fma_f32 v241, v59, v241, 1.0
	v_sub_f32_e32 v240, 1.0, v240
	v_mul_f32_e64 v241, v241, -v59
	v_cndmask_b32_e32 v101, v241, v240, vcc
	v_and_b32_e32 v59, 0xffff0000, v128
	v_mul_f32_e32 v23, v23, v59
	v_add_f32_e32 v102, v23, v23
	s_mov_b32 s0, 0xbca3d70a
	v_cmp_nlt_f32_e32 vcc, s0, v102
	s_and_saveexec_b64 s[0:1], vcc
	s_xor_b64 s[0:1], exec, s[0:1]
	v_mul_f32_e32 v59, 0x3fb8aa3b, v102
	v_exp_f32_e32 v59, v59
	s_nop 0
	v_sub_f32_e32 v59, 1.0, v59
	s_andn2_saveexec_b64 s[0:1], s[0:1]
	s_cbranch_execz .LBB0_1035
	s_mov_b32 s2, 0x3e2aaaab
	v_fma_f32 v59, v102, s2, 0.5
	v_fma_f32 v59, v102, v59, 1.0
	v_mul_f32_e64 v59, v59, -v102
	s_branch .LBB0_1035
